# v077 with the fragment ds_reads issued first in every load segment (SALU address/M0 work moved behind them, before the LDS-DMA loads)
# baseline (speedup 1.0000x reference)
.LBB0_134:
	ds_read_b128 v[128:131], v172
	ds_read_b128 v[132:135], v172 offset:1024
	ds_read_b128 v[148:151], v172 offset:2048
	ds_read_b128 v[152:155], v172 offset:3072
	ds_read_b128 v[156:159], v192
	ds_read_b128 v[164:167], v192 offset:2048
	ds_read_b128 v[194:197], v192 offset:4096
	ds_read_b128 v[202:205], v192 offset:6144
	ds_read_b128 v[160:163], v192 offset:1024
	ds_read_b128 v[168:171], v192 offset:3072
	ds_read_b128 v[198:201], v192 offset:5120
	ds_read_b128 v[206:209], v192 offset:7168
	s_add_u32 s28, s66, 0xfffc0080
	s_addc_u32 s29, s67, -1
	s_add_i32 s88, 0, 0x10000
	s_cmp_eq_u32 vcc_lo, 12
	s_cselect_b32 s71, s5, s29
	s_cselect_b32 s70, s7, s28
	s_cselect_b32 s69, s17, s91
	s_cselect_b32 s68, s19, s85
	s_add_i32 m0, s73, 0xc000
	s_nop 0
	global_load_lds_dwordx4 v144, s[66:67]
	s_add_i32 m0, s73, 0xe000
	s_nop 0
	global_load_lds_dwordx4 v146, s[66:67]
	s_waitcnt lgkmcnt(8)
	s_barrier
	s_waitcnt lgkmcnt(7)
	v_mfma_f32_16x16x32_bf16 v[124:127], v[128:131], v[156:159], v[124:127]
	v_mfma_f32_16x16x32_bf16 v[120:123], v[148:151], v[156:159], v[120:123]
	s_waitcnt lgkmcnt(6)
	v_mfma_f32_16x16x32_bf16 v[108:111], v[128:131], v[164:167], v[108:111]
	v_mfma_f32_16x16x32_bf16 v[104:107], v[148:151], v[164:167], v[104:107]
	s_waitcnt lgkmcnt(5)
	v_mfma_f32_16x16x32_bf16 v[92:95], v[128:131], v[194:197], v[92:95]
	v_mfma_f32_16x16x32_bf16 v[88:91], v[148:151], v[194:197], v[88:91]
	s_waitcnt lgkmcnt(4)
	v_mfma_f32_16x16x32_bf16 v[76:79], v[128:131], v[202:205], v[76:79]
	v_mfma_f32_16x16x32_bf16 v[72:75], v[148:151], v[202:205], v[72:75]
	s_waitcnt lgkmcnt(3)
	v_mfma_f32_16x16x32_bf16 v[124:127], v[132:135], v[160:163], v[124:127]
	v_mfma_f32_16x16x32_bf16 v[120:123], v[152:155], v[160:163], v[120:123]
	s_waitcnt lgkmcnt(2)
	v_mfma_f32_16x16x32_bf16 v[108:111], v[132:135], v[168:171], v[108:111]
	v_mfma_f32_16x16x32_bf16 v[104:107], v[152:155], v[168:171], v[104:107]
	s_waitcnt lgkmcnt(1)
	v_mfma_f32_16x16x32_bf16 v[92:95], v[132:135], v[198:201], v[92:95]
	v_mfma_f32_16x16x32_bf16 v[88:91], v[152:155], v[198:201], v[88:91]
	s_waitcnt lgkmcnt(0)
	v_mfma_f32_16x16x32_bf16 v[76:79], v[132:135], v[206:209], v[76:79]
	v_mfma_f32_16x16x32_bf16 v[72:75], v[152:155], v[206:209], v[72:75]
	s_barrier
	ds_read_b128 v[210:213], v172 offset:16384
	ds_read_b128 v[214:217], v172 offset:17408
	ds_read_b128 v[232:235], v172 offset:18432
	ds_read_b128 v[236:239], v172 offset:19456
	s_add_i32 s89, 0, 0x14000
	s_add_i32 s28, s88, s72
	s_mov_b32 m0, s28
	s_nop 0
	global_load_lds_dwordx4 v138, s[68:69]
	s_add_i32 m0, s28, 0x2000
	s_nop 0
	global_load_lds_dwordx4 v142, s[68:69]
	s_barrier
	s_waitcnt lgkmcnt(3)
	v_mfma_f32_16x16x32_bf16 v[116:119], v[210:213], v[156:159], v[116:119]
	s_waitcnt lgkmcnt(1)
	v_mfma_f32_16x16x32_bf16 v[112:115], v[232:235], v[156:159], v[112:115]
	v_mfma_f32_16x16x32_bf16 v[100:103], v[210:213], v[164:167], v[100:103]
	v_mfma_f32_16x16x32_bf16 v[96:99], v[232:235], v[164:167], v[96:99]
	v_mfma_f32_16x16x32_bf16 v[84:87], v[210:213], v[194:197], v[84:87]
	v_mfma_f32_16x16x32_bf16 v[80:83], v[232:235], v[194:197], v[80:83]
	v_mfma_f32_16x16x32_bf16 v[68:71], v[210:213], v[202:205], v[68:71]
	v_mfma_f32_16x16x32_bf16 v[64:67], v[232:235], v[202:205], v[64:67]
	v_mfma_f32_16x16x32_bf16 v[116:119], v[214:217], v[160:163], v[116:119]
	s_waitcnt lgkmcnt(0)
	v_mfma_f32_16x16x32_bf16 v[112:115], v[236:239], v[160:163], v[112:115]
	v_mfma_f32_16x16x32_bf16 v[100:103], v[214:217], v[168:171], v[100:103]
	v_mfma_f32_16x16x32_bf16 v[96:99], v[236:239], v[168:171], v[96:99]
	v_mfma_f32_16x16x32_bf16 v[84:87], v[214:217], v[198:201], v[84:87]
	v_mfma_f32_16x16x32_bf16 v[80:83], v[236:239], v[198:201], v[80:83]
	v_mfma_f32_16x16x32_bf16 v[68:71], v[214:217], v[206:209], v[68:71]
	v_mfma_f32_16x16x32_bf16 v[64:67], v[236:239], v[206:209], v[64:67]
	s_mov_b32 m0, s73
	s_barrier
	ds_read_b128 v[156:159], v192 offset:16384
	ds_read_b128 v[164:167], v192 offset:18432
	ds_read_b128 v[194:197], v192 offset:20480
	ds_read_b128 v[202:205], v192 offset:22528
	ds_read_b128 v[160:163], v192 offset:17408
	ds_read_b128 v[168:171], v192 offset:19456
	ds_read_b128 v[198:201], v192 offset:21504
	ds_read_b128 v[206:209], v192 offset:23552
	global_load_lds_dwordx4 v136, s[70:71]
	s_mov_b32 m0, s74
	s_nop 0
	global_load_lds_dwordx4 v140, s[70:71]
	s_barrier
	s_waitcnt lgkmcnt(7)
	v_mfma_f32_16x16x32_bf16 v[60:63], v[128:131], v[156:159], v[60:63]
	v_mfma_f32_16x16x32_bf16 v[56:59], v[148:151], v[156:159], v[56:59]
	s_waitcnt lgkmcnt(6)
	v_mfma_f32_16x16x32_bf16 v[44:47], v[128:131], v[164:167], v[44:47]
	v_mfma_f32_16x16x32_bf16 v[40:43], v[148:151], v[164:167], v[40:43]
	s_waitcnt lgkmcnt(5)
	v_mfma_f32_16x16x32_bf16 v[28:31], v[128:131], v[194:197], v[28:31]
	v_mfma_f32_16x16x32_bf16 v[24:27], v[148:151], v[194:197], v[24:27]
	s_waitcnt lgkmcnt(4)
	v_mfma_f32_16x16x32_bf16 v[12:15], v[128:131], v[202:205], v[12:15]
	v_mfma_f32_16x16x32_bf16 v[8:11], v[148:151], v[202:205], v[8:11]
	s_waitcnt lgkmcnt(3)
	v_mfma_f32_16x16x32_bf16 v[60:63], v[132:135], v[160:163], v[60:63]
	v_mfma_f32_16x16x32_bf16 v[56:59], v[152:155], v[160:163], v[56:59]
	s_waitcnt lgkmcnt(2)
	v_mfma_f32_16x16x32_bf16 v[44:47], v[132:135], v[168:171], v[44:47]
	v_mfma_f32_16x16x32_bf16 v[40:43], v[152:155], v[168:171], v[40:43]
	s_waitcnt lgkmcnt(1)
	v_mfma_f32_16x16x32_bf16 v[28:31], v[132:135], v[198:201], v[28:31]
	v_mfma_f32_16x16x32_bf16 v[24:27], v[152:155], v[198:201], v[24:27]
	s_waitcnt lgkmcnt(0)
	v_mfma_f32_16x16x32_bf16 v[12:15], v[132:135], v[206:209], v[12:15]
	v_mfma_f32_16x16x32_bf16 v[8:11], v[152:155], v[206:209], v[8:11]
	s_barrier
	s_add_u32 s28, s68, 0x40000
	s_addc_u32 s29, s69, 0
	s_add_i32 s88, s89, s72
	s_mov_b32 m0, s88
	s_nop 0
	global_load_lds_dwordx4 v138, s[28:29]
	s_add_i32 m0, s88, 0x2000
	s_nop 0
	global_load_lds_dwordx4 v142, s[28:29]
	s_waitcnt vmcnt(6)
	s_barrier
	v_mfma_f32_16x16x32_bf16 v[52:55], v[210:213], v[156:159], v[52:55]
	v_mfma_f32_16x16x32_bf16 v[48:51], v[232:235], v[156:159], v[48:51]
	v_mfma_f32_16x16x32_bf16 v[36:39], v[210:213], v[164:167], v[36:39]
	v_mfma_f32_16x16x32_bf16 v[32:35], v[232:235], v[164:167], v[32:35]
	v_mfma_f32_16x16x32_bf16 v[20:23], v[210:213], v[194:197], v[20:23]
	v_mfma_f32_16x16x32_bf16 v[16:19], v[232:235], v[194:197], v[16:19]
	v_mfma_f32_16x16x32_bf16 v[4:7], v[210:213], v[202:205], v[4:7]
	v_mfma_f32_16x16x32_bf16 v[0:3], v[232:235], v[202:205], v[0:3]
	v_mfma_f32_16x16x32_bf16 v[52:55], v[214:217], v[160:163], v[52:55]
	v_mfma_f32_16x16x32_bf16 v[48:51], v[236:239], v[160:163], v[48:51]
	v_mfma_f32_16x16x32_bf16 v[36:39], v[214:217], v[168:171], v[36:39]
	v_mfma_f32_16x16x32_bf16 v[32:35], v[236:239], v[168:171], v[32:35]
	v_mfma_f32_16x16x32_bf16 v[20:23], v[214:217], v[198:201], v[20:23]
	v_mfma_f32_16x16x32_bf16 v[16:19], v[236:239], v[198:201], v[16:19]
	v_mfma_f32_16x16x32_bf16 v[4:7], v[214:217], v[206:209], v[4:7]
	v_mfma_f32_16x16x32_bf16 v[0:3], v[236:239], v[206:209], v[0:3]
	s_add_i32 s88, 0, 0x18000
	s_barrier
	ds_read_b128 v[128:131], v172 offset:32768
	ds_read_b128 v[132:135], v172 offset:33792
	ds_read_b128 v[148:151], v172 offset:34816
	ds_read_b128 v[152:155], v172 offset:35840
	ds_read_b128 v[156:159], v192 offset:32768
	ds_read_b128 v[164:167], v192 offset:34816
	ds_read_b128 v[194:197], v192 offset:36864
	ds_read_b128 v[202:205], v192 offset:38912
	ds_read_b128 v[160:163], v192 offset:33792
	ds_read_b128 v[168:171], v192 offset:35840
	ds_read_b128 v[198:201], v192 offset:37888
	ds_read_b128 v[206:209], v192 offset:39936
	s_add_u32 s28, s70, 0x40000
	s_addc_u32 s29, s71, 0
	s_mov_b32 m0, s75
	s_nop 0
	global_load_lds_dwordx4 v136, s[28:29]
	s_mov_b32 m0, s76
	s_nop 0
	global_load_lds_dwordx4 v140, s[28:29]
	s_waitcnt lgkmcnt(8)
	s_barrier
	s_waitcnt lgkmcnt(7)
	v_mfma_f32_16x16x32_bf16 v[124:127], v[128:131], v[156:159], v[124:127]
	v_mfma_f32_16x16x32_bf16 v[120:123], v[148:151], v[156:159], v[120:123]
	s_waitcnt lgkmcnt(6)
	v_mfma_f32_16x16x32_bf16 v[108:111], v[128:131], v[164:167], v[108:111]
	v_mfma_f32_16x16x32_bf16 v[104:107], v[148:151], v[164:167], v[104:107]
	s_waitcnt lgkmcnt(5)
	v_mfma_f32_16x16x32_bf16 v[92:95], v[128:131], v[194:197], v[92:95]
	v_mfma_f32_16x16x32_bf16 v[88:91], v[148:151], v[194:197], v[88:91]
	s_waitcnt lgkmcnt(4)
	v_mfma_f32_16x16x32_bf16 v[76:79], v[128:131], v[202:205], v[76:79]
	v_mfma_f32_16x16x32_bf16 v[72:75], v[148:151], v[202:205], v[72:75]
	s_waitcnt lgkmcnt(3)
	v_mfma_f32_16x16x32_bf16 v[124:127], v[132:135], v[160:163], v[124:127]
	v_mfma_f32_16x16x32_bf16 v[120:123], v[152:155], v[160:163], v[120:123]
	s_waitcnt lgkmcnt(2)
	v_mfma_f32_16x16x32_bf16 v[108:111], v[132:135], v[168:171], v[108:111]
	v_mfma_f32_16x16x32_bf16 v[104:107], v[152:155], v[168:171], v[104:107]
	s_waitcnt lgkmcnt(1)
	v_mfma_f32_16x16x32_bf16 v[92:95], v[132:135], v[198:201], v[92:95]
	v_mfma_f32_16x16x32_bf16 v[88:91], v[152:155], v[198:201], v[88:91]
	s_waitcnt lgkmcnt(0)
	v_mfma_f32_16x16x32_bf16 v[76:79], v[132:135], v[206:209], v[76:79]
	v_mfma_f32_16x16x32_bf16 v[72:75], v[152:155], v[206:209], v[72:75]
	s_barrier
	ds_read_b128 v[210:213], v172 offset:49152
	ds_read_b128 v[214:217], v172 offset:50176
	ds_read_b128 v[232:235], v172 offset:51200
	ds_read_b128 v[236:239], v172 offset:52224
	s_add_i32 s98, 0, 0x1c000
	s_add_i32 s28, s88, s72
	s_add_i32 m0, s28, 0xffffff80
	s_nop 0
	global_load_lds_dwordx4 v138, s[68:69] offset:128
	s_add_i32 m0, s28, 0x1f80
	s_nop 0
	global_load_lds_dwordx4 v142, s[68:69] offset:128
	s_barrier
	s_waitcnt lgkmcnt(3)
	v_mfma_f32_16x16x32_bf16 v[116:119], v[210:213], v[156:159], v[116:119]
	s_waitcnt lgkmcnt(1)
	v_mfma_f32_16x16x32_bf16 v[112:115], v[232:235], v[156:159], v[112:115]
	v_mfma_f32_16x16x32_bf16 v[100:103], v[210:213], v[164:167], v[100:103]
	v_mfma_f32_16x16x32_bf16 v[96:99], v[232:235], v[164:167], v[96:99]
	v_mfma_f32_16x16x32_bf16 v[84:87], v[210:213], v[194:197], v[84:87]
	v_mfma_f32_16x16x32_bf16 v[80:83], v[232:235], v[194:197], v[80:83]
	v_mfma_f32_16x16x32_bf16 v[68:71], v[210:213], v[202:205], v[68:71]
	v_mfma_f32_16x16x32_bf16 v[64:67], v[232:235], v[202:205], v[64:67]
	v_mfma_f32_16x16x32_bf16 v[116:119], v[214:217], v[160:163], v[116:119]
	s_waitcnt lgkmcnt(0)
	v_mfma_f32_16x16x32_bf16 v[112:115], v[236:239], v[160:163], v[112:115]
	v_mfma_f32_16x16x32_bf16 v[100:103], v[214:217], v[168:171], v[100:103]
	v_mfma_f32_16x16x32_bf16 v[96:99], v[236:239], v[168:171], v[96:99]
	v_mfma_f32_16x16x32_bf16 v[84:87], v[214:217], v[198:201], v[84:87]
	v_mfma_f32_16x16x32_bf16 v[80:83], v[236:239], v[198:201], v[80:83]
	v_mfma_f32_16x16x32_bf16 v[68:71], v[214:217], v[206:209], v[68:71]
	v_mfma_f32_16x16x32_bf16 v[64:67], v[236:239], v[206:209], v[64:67]
	s_add_i32 m0, s79, 0xffffff80
	s_barrier
	ds_read_b128 v[156:159], v192 offset:49152
	ds_read_b128 v[164:167], v192 offset:51200
	ds_read_b128 v[194:197], v192 offset:53248
	ds_read_b128 v[202:205], v192 offset:55296
	ds_read_b128 v[160:163], v192 offset:50176
	ds_read_b128 v[168:171], v192 offset:52224
	ds_read_b128 v[198:201], v192 offset:54272
	ds_read_b128 v[206:209], v192 offset:56320
	global_load_lds_dwordx4 v136, s[70:71] offset:128
	s_add_i32 m0, s80, 0xffffff80
	s_nop 0
	global_load_lds_dwordx4 v140, s[70:71] offset:128
	s_barrier
	s_waitcnt lgkmcnt(7)
	v_mfma_f32_16x16x32_bf16 v[60:63], v[128:131], v[156:159], v[60:63]
	v_mfma_f32_16x16x32_bf16 v[56:59], v[148:151], v[156:159], v[56:59]
	s_waitcnt lgkmcnt(6)
	v_mfma_f32_16x16x32_bf16 v[44:47], v[128:131], v[164:167], v[44:47]
	v_mfma_f32_16x16x32_bf16 v[40:43], v[148:151], v[164:167], v[40:43]
	s_waitcnt lgkmcnt(5)
	v_mfma_f32_16x16x32_bf16 v[28:31], v[128:131], v[194:197], v[28:31]
	v_mfma_f32_16x16x32_bf16 v[24:27], v[148:151], v[194:197], v[24:27]
	s_waitcnt lgkmcnt(4)
	v_mfma_f32_16x16x32_bf16 v[12:15], v[128:131], v[202:205], v[12:15]
	v_mfma_f32_16x16x32_bf16 v[8:11], v[148:151], v[202:205], v[8:11]
	s_waitcnt lgkmcnt(3)
	v_mfma_f32_16x16x32_bf16 v[60:63], v[132:135], v[160:163], v[60:63]
	v_mfma_f32_16x16x32_bf16 v[56:59], v[152:155], v[160:163], v[56:59]
	s_waitcnt lgkmcnt(2)
	v_mfma_f32_16x16x32_bf16 v[44:47], v[132:135], v[168:171], v[44:47]
	v_mfma_f32_16x16x32_bf16 v[40:43], v[152:155], v[168:171], v[40:43]
	s_waitcnt lgkmcnt(1)
	v_mfma_f32_16x16x32_bf16 v[28:31], v[132:135], v[198:201], v[28:31]
	v_mfma_f32_16x16x32_bf16 v[24:27], v[152:155], v[198:201], v[24:27]
	s_waitcnt lgkmcnt(0)
	v_mfma_f32_16x16x32_bf16 v[12:15], v[132:135], v[206:209], v[12:15]
	v_mfma_f32_16x16x32_bf16 v[8:11], v[152:155], v[206:209], v[8:11]
	s_barrier
	s_add_u32 s28, s68, 0x40080
	s_addc_u32 s29, s69, 0
	s_add_i32 s68, s98, s72
	s_mov_b32 m0, s68
	s_nop 0
	global_load_lds_dwordx4 v138, s[28:29]
	s_add_i32 m0, s68, 0x2000
	s_nop 0
	global_load_lds_dwordx4 v142, s[28:29]
	s_waitcnt vmcnt(6)
	s_barrier
	v_mfma_f32_16x16x32_bf16 v[52:55], v[210:213], v[156:159], v[52:55]
	v_mfma_f32_16x16x32_bf16 v[48:51], v[232:235], v[156:159], v[48:51]
	v_mfma_f32_16x16x32_bf16 v[36:39], v[210:213], v[164:167], v[36:39]
	v_mfma_f32_16x16x32_bf16 v[32:35], v[232:235], v[164:167], v[32:35]
	v_mfma_f32_16x16x32_bf16 v[20:23], v[210:213], v[194:197], v[20:23]
	v_mfma_f32_16x16x32_bf16 v[16:19], v[232:235], v[194:197], v[16:19]
	v_mfma_f32_16x16x32_bf16 v[4:7], v[210:213], v[202:205], v[4:7]
	v_mfma_f32_16x16x32_bf16 v[0:3], v[232:235], v[202:205], v[0:3]
	v_mfma_f32_16x16x32_bf16 v[52:55], v[214:217], v[160:163], v[52:55]
	v_mfma_f32_16x16x32_bf16 v[48:51], v[236:239], v[160:163], v[48:51]
	v_mfma_f32_16x16x32_bf16 v[36:39], v[214:217], v[168:171], v[36:39]
	v_mfma_f32_16x16x32_bf16 v[32:35], v[236:239], v[168:171], v[32:35]
	v_mfma_f32_16x16x32_bf16 v[20:23], v[214:217], v[198:201], v[20:23]
	v_mfma_f32_16x16x32_bf16 v[16:19], v[236:239], v[198:201], v[16:19]
	v_mfma_f32_16x16x32_bf16 v[4:7], v[214:217], v[206:209], v[4:7]
	v_mfma_f32_16x16x32_bf16 v[0:3], v[236:239], v[206:209], v[0:3]
	s_add_i32 vcc_lo, vcc_lo, 2
	s_add_u32 s66, s66, 0x100
	s_addc_u32 s67, s67, 0
	s_add_u32 s85, s85, 0x100
	s_addc_u32 s91, s91, 0
	s_cmp_lt_u32 vcc_lo, 14
	s_barrier
	s_cbranch_scc1 .LBB0_134
	s_lshl_b32 s4, s4, 8
	v_mov_b32_e32 v176, v175
	v_mov_b32_e32 v188, v190
	s_add_i32 s4, s4, s77
	s_cmp_gt_i32 s6, 7
	v_add_u32_e32 v148, s4, v176
	v_lshlrev_b32_e32 v128, 2, v188
	v_ashrrev_i32_e32 v129, 31, v128
	v_ashrrev_i32_e32 v149, 31, v148
	v_lshl_add_u64 v[128:129], v[128:129], 2, s[8:9]
	v_lshlrev_b64 v[130:131], 6, v[148:149]
	v_add_u32_e32 v166, 16, v148
	v_lshl_add_u64 v[130:131], v[128:129], 0, v[130:131]
	v_ashrrev_i32_e32 v167, 31, v166
	global_load_dwordx4 v[160:163], v[130:131], off
	v_lshlrev_b64 v[130:131], 6, v[166:167]
	v_lshl_add_u64 v[130:131], v[128:129], 0, v[130:131]
	global_load_dwordx4 v[168:171], v[130:131], off
	v_add_u32_e32 v164, 32, v148
	v_ashrrev_i32_e32 v165, 31, v164
	v_lshlrev_b64 v[130:131], 6, v[164:165]
	v_add_u32_e32 v158, 48, v148
	v_lshl_add_u64 v[130:131], v[128:129], 0, v[130:131]
	v_ashrrev_i32_e32 v159, 31, v158
	global_load_dwordx4 v[194:197], v[130:131], off
	v_lshlrev_b64 v[130:131], 6, v[158:159]
	v_lshl_add_u64 v[130:131], v[128:129], 0, v[130:131]
	global_load_dwordx4 v[198:201], v[130:131], off
	v_add_u32_e32 v156, 0x80, v148
	v_ashrrev_i32_e32 v157, 31, v156
	v_lshlrev_b64 v[130:131], 6, v[156:157]
	v_add_u32_e32 v154, 0x90, v148
	v_lshl_add_u64 v[130:131], v[128:129], 0, v[130:131]
	v_ashrrev_i32_e32 v155, 31, v154
	global_load_dwordx4 v[202:205], v[130:131], off
	v_lshlrev_b64 v[130:131], 6, v[154:155]
	v_add_u32_e32 v152, 0xa0, v148
	v_lshl_add_u64 v[130:131], v[128:129], 0, v[130:131]
	v_ashrrev_i32_e32 v153, 31, v152
	global_load_dwordx4 v[206:209], v[130:131], off
	v_lshlrev_b64 v[130:131], 6, v[152:153]
	v_add_u32_e32 v150, 0xb0, v148
	v_lshl_add_u64 v[130:131], v[128:129], 0, v[130:131]
	v_ashrrev_i32_e32 v151, 31, v150
	global_load_dwordx4 v[132:135], v[130:131], off
	v_lshlrev_b64 v[130:131], 6, v[150:151]
	v_lshl_add_u64 v[128:129], v[128:129], 0, v[130:131]
	global_load_dwordx4 v[128:131], v[128:129], off
	s_cselect_b64 s[66:67], -1, 0
	s_lshl_b32 s7, s6, 8
	s_add_i32 s7, s81, s7
	s_cmp_lt_i32 s6, 8
	s_mov_b64 s[68:69], -1
	s_waitcnt vmcnt(0)
	v_mov_b32_e32 v172, v161
	v_mov_b32_e32 v173, v162
	v_mov_b32_e32 v161, v163
	v_mov_b32_e32 v162, v169
	v_mov_b32_e32 v163, v170
	v_mov_b32_e32 v169, v171
	v_pk_add_f32 v[160:161], v[172:173], v[160:161]
	v_pk_add_f32 v[162:163], v[162:163], v[168:169]
	v_mov_b32_e32 v169, v160
	v_mov_b32_e32 v168, v162
	v_mov_b32_e32 v160, v163
	v_pk_add_f32 v[160:161], v[168:169], v[160:161]
	v_mov_b32_e32 v163, v161
	v_mov_b32_e32 v162, v160
	s_waitcnt lgkmcnt(0)
	s_nop 0
	v_permlane16_swap_b32 v161, v163
	v_permlane16_swap_b32 v160, v162
	v_pk_add_f32 v[160:161], v[160:161], v[162:163]
	v_mov_b32_e32 v163, v161
	v_mov_b32_e32 v162, v160
	s_waitcnt lgkmcnt(0)
	s_nop 0
	v_permlane32_swap_b32 v161, v163
	v_permlane32_swap_b32 v160, v162
	v_pk_add_f32 v[160:161], v[160:161], v[162:163]
	s_nop 0
	v_pk_fma_f32 v[172:173], v[160:161], s[30:31], v[178:179] op_sel_hi:[1,0,0]
	v_mov_b32_e32 v162, v199
	v_mul_f32_e32 v160, 0x4b800000, v173
	v_cmp_gt_f32_e32 vcc, s86, v173
	v_mov_b32_e32 v163, v200
	v_mov_b32_e32 v199, v201
	v_cndmask_b32_e32 v160, v173, v160, vcc
	v_rsq_f32_e32 v160, v160
	v_pk_add_f32 v[162:163], v[162:163], v[198:199]
	v_cmp_gt_f32_e64 s[4:5], s86, v172
	v_mov_b32_e32 v168, v162
	v_mul_f32_e32 v161, 0x45800000, v160
	v_cndmask_b32_e32 v174, v160, v161, vcc
	v_mov_b32_e32 v160, v195
	v_mov_b32_e32 v161, v196
	v_mov_b32_e32 v195, v197
	v_pk_add_f32 v[160:161], v[160:161], v[194:195]
	s_nop 0
	v_mov_b32_e32 v169, v160
	v_mov_b32_e32 v160, v163
	v_pk_add_f32 v[160:161], v[168:169], v[160:161]
	v_mov_b32_e32 v163, v161
	v_mov_b32_e32 v162, v160
	s_waitcnt lgkmcnt(0)
	s_nop 0
	v_permlane16_swap_b32 v161, v163
	v_permlane16_swap_b32 v160, v162
	v_pk_add_f32 v[168:169], v[160:161], v[162:163]
	v_mov_b32_e32 v160, v203
	v_mov_b32_e32 v161, v204
	v_mov_b32_e32 v203, v205
	v_mov_b32_e32 v162, v207
	v_mov_b32_e32 v163, v208
	v_mov_b32_e32 v207, v209
	v_pk_add_f32 v[160:161], v[160:161], v[202:203]
	v_pk_add_f32 v[162:163], v[162:163], v[206:207]
	v_mov_b32_e32 v195, v160
	v_mov_b32_e32 v194, v162
	v_mov_b32_e32 v160, v163
	v_pk_add_f32 v[160:161], v[194:195], v[160:161]
	v_mov_b32_e32 v194, v133
	v_mov_b32_e32 v195, v134
	v_mov_b32_e32 v133, v135
	v_mov_b32_e32 v134, v129
	v_mov_b32_e32 v135, v130
	v_mov_b32_e32 v129, v131
	v_pk_add_f32 v[132:133], v[194:195], v[132:133]
	v_pk_add_f32 v[128:129], v[134:135], v[128:129]
	v_mov_b32_e32 v131, v132
	v_mov_b32_e32 v130, v128
	v_mov_b32_e32 v132, v129
	v_pk_add_f32 v[128:129], v[130:131], v[132:133]
	v_mov_b32_e32 v163, v161
	v_mov_b32_e32 v162, v160
	ds_bpermute_b32 v131, v219, v129
	v_mov_b32_e32 v130, v128
	ds_bpermute_b32 v171, v218, v169
	ds_bpermute_b32 v170, v218, v168
	s_waitcnt lgkmcnt(3)
	v_permlane16_swap_b32 v161, v163
	v_permlane16_swap_b32 v160, v162
	v_pk_add_f32 v[160:161], v[160:161], v[162:163]
	ds_bpermute_b32 v163, v218, v161
	s_waitcnt lgkmcnt(3)
	v_permlane16_swap_b32 v128, v130
	v_pk_add_f32 v[132:133], v[128:129], v[130:131]
	ds_bpermute_b32 v162, v218, v160
	ds_bpermute_b32 v135, v218, v133
	ds_bpermute_b32 v134, v218, v132
	v_lshlrev_b32_e32 v128, 3, v188
	v_add_u32_e32 v130, s7, v128
	v_lshlrev_b64 v[188:189], 11, v[148:149]
	v_ashrrev_i32_e32 v131, 31, v130
	s_cbranch_scc1 .LBB0_137
	v_mul_f32_e32 v196, v120, v174
	v_mul_f32_e32 v197, v121, v174
	v_mul_f32_e32 v198, v122, v174
	v_mul_f32_e32 v199, v123, v174
	v_mul_f32_e32 v129, v124, v174
	v_mul_f32_e32 v149, v125, v174
	v_mul_f32_e32 v173, v126, v174
	v_mul_f32_e32 v193, v127, v174
	v_cvt_pk_bf16_f32 v194, v129, v149
	v_cvt_pk_bf16_f32 v195, v173, v193
	v_cvt_pk_bf16_f32 v196, v196, v197
	v_cvt_pk_bf16_f32 v197, v198, v199
	v_lshl_add_u64 v[198:199], s[12:13], 0, v[188:189]
	v_lshl_add_u64 v[198:199], v[130:131], 1, v[198:199]
	global_store_dwordx4 v[198:199], v[194:197], off
	s_mov_b64 s[68:69], 0
	v_mul_f32_e32 v129, v116, v174
	v_mul_f32_e32 v196, v112, v174
	v_mul_f32_e32 v197, v113, v174
	v_mul_f32_e32 v149, v117, v174
	v_mul_f32_e32 v173, v118, v174
	v_mul_f32_e32 v193, v119, v174
	v_mul_f32_e32 v200, v114, v174
	v_mul_f32_e32 v201, v115, v174
	v_cvt_pk_bf16_f32 v194, v129, v149
	v_cvt_pk_bf16_f32 v195, v173, v193
	v_cvt_pk_bf16_f32 v196, v196, v197
	v_cvt_pk_bf16_f32 v197, v200, v201
	global_store_dwordx4 v[198:199], v[194:197], off offset:256

.LBB0_413:
	ds_read_b128 v[128:131], v174
	ds_read_b128 v[132:135], v174 offset:1024
	ds_read_b128 v[136:139], v174 offset:2048
	ds_read_b128 v[140:143], v174 offset:3072
	ds_read_b128 v[154:157], v165
	ds_read_b128 v[166:169], v165 offset:2048
	ds_read_b128 v[188:191], v165 offset:4096
	ds_read_b128 v[196:199], v165 offset:6144
	ds_read_b128 v[158:161], v165 offset:1024
	ds_read_b128 v[170:173], v165 offset:3072
	ds_read_b128 v[192:195], v165 offset:5120
	ds_read_b128 v[200:203], v165 offset:7168
	s_add_i32 vcc_lo, s62, 2
	s_add_u32 s4, s18, 0x100
	s_addc_u32 s5, s19, 0
	s_add_i32 s28, 0, 0x10000
	s_cmp_eq_u32 s13, s62
	s_cselect_b32 s62, s6, s85
	s_cselect_b32 s65, s17, s5
	s_cselect_b32 s64, s16, s4
	s_cselect_b32 s63, s7, s91
	s_add_i32 m0, s69, 0xc000
	s_nop 0
	global_load_lds_dwordx4 v150, s[18:19]
	s_add_i32 m0, s69, 0xe000
	s_nop 0
	global_load_lds_dwordx4 v152, s[18:19]
	s_waitcnt lgkmcnt(8)
	s_barrier
	s_waitcnt lgkmcnt(7)
	v_mfma_f32_16x16x32_bf16 v[124:127], v[128:131], v[154:157], v[124:127]
	v_mfma_f32_16x16x32_bf16 v[120:123], v[136:139], v[154:157], v[120:123]
	s_waitcnt lgkmcnt(6)
	v_mfma_f32_16x16x32_bf16 v[108:111], v[128:131], v[166:169], v[108:111]
	v_mfma_f32_16x16x32_bf16 v[104:107], v[136:139], v[166:169], v[104:107]
	s_waitcnt lgkmcnt(5)
	v_mfma_f32_16x16x32_bf16 v[92:95], v[128:131], v[188:191], v[92:95]
	v_mfma_f32_16x16x32_bf16 v[88:91], v[136:139], v[188:191], v[88:91]
	s_waitcnt lgkmcnt(4)
	v_mfma_f32_16x16x32_bf16 v[76:79], v[128:131], v[196:199], v[76:79]
	v_mfma_f32_16x16x32_bf16 v[72:75], v[136:139], v[196:199], v[72:75]
	s_waitcnt lgkmcnt(3)
	v_mfma_f32_16x16x32_bf16 v[124:127], v[132:135], v[158:161], v[124:127]
	v_mfma_f32_16x16x32_bf16 v[120:123], v[140:143], v[158:161], v[120:123]
	s_waitcnt lgkmcnt(2)
	v_mfma_f32_16x16x32_bf16 v[108:111], v[132:135], v[170:173], v[108:111]
	v_mfma_f32_16x16x32_bf16 v[104:107], v[140:143], v[170:173], v[104:107]
	s_waitcnt lgkmcnt(1)
	v_mfma_f32_16x16x32_bf16 v[92:95], v[132:135], v[192:195], v[92:95]
	v_mfma_f32_16x16x32_bf16 v[88:91], v[140:143], v[192:195], v[88:91]
	s_waitcnt lgkmcnt(0)
	v_mfma_f32_16x16x32_bf16 v[76:79], v[132:135], v[200:203], v[76:79]
	v_mfma_f32_16x16x32_bf16 v[72:75], v[140:143], v[200:203], v[72:75]
	s_barrier
	ds_read_b128 v[204:207], v174 offset:16384
	ds_read_b128 v[208:211], v174 offset:17408
	ds_read_b128 v[212:215], v174 offset:18432
	ds_read_b128 v[232:235], v174 offset:19456
	s_add_i32 s29, 0, 0x14000
	s_add_i32 s18, s28, s68
	s_mov_b32 m0, s18
	s_nop 0
	global_load_lds_dwordx4 v176, s[62:63]
	s_add_i32 m0, s18, 0x2000
	s_nop 0
	global_load_lds_dwordx4 v148, s[62:63]
	s_barrier
	s_waitcnt lgkmcnt(3)
	v_mfma_f32_16x16x32_bf16 v[116:119], v[204:207], v[154:157], v[116:119]
	s_waitcnt lgkmcnt(1)
	v_mfma_f32_16x16x32_bf16 v[112:115], v[212:215], v[154:157], v[112:115]
	v_mfma_f32_16x16x32_bf16 v[100:103], v[204:207], v[166:169], v[100:103]
	v_mfma_f32_16x16x32_bf16 v[96:99], v[212:215], v[166:169], v[96:99]
	v_mfma_f32_16x16x32_bf16 v[84:87], v[204:207], v[188:191], v[84:87]
	v_mfma_f32_16x16x32_bf16 v[80:83], v[212:215], v[188:191], v[80:83]
	v_mfma_f32_16x16x32_bf16 v[68:71], v[204:207], v[196:199], v[68:71]
	v_mfma_f32_16x16x32_bf16 v[64:67], v[212:215], v[196:199], v[64:67]
	v_mfma_f32_16x16x32_bf16 v[116:119], v[208:211], v[158:161], v[116:119]
	s_waitcnt lgkmcnt(0)
	v_mfma_f32_16x16x32_bf16 v[112:115], v[232:235], v[158:161], v[112:115]
	v_mfma_f32_16x16x32_bf16 v[100:103], v[208:211], v[170:173], v[100:103]
	v_mfma_f32_16x16x32_bf16 v[96:99], v[232:235], v[170:173], v[96:99]
	v_mfma_f32_16x16x32_bf16 v[84:87], v[208:211], v[192:195], v[84:87]
	v_mfma_f32_16x16x32_bf16 v[80:83], v[232:235], v[192:195], v[80:83]
	v_mfma_f32_16x16x32_bf16 v[68:71], v[208:211], v[200:203], v[68:71]
	v_mfma_f32_16x16x32_bf16 v[64:67], v[232:235], v[200:203], v[64:67]
	s_mov_b32 m0, s69
	s_barrier
	ds_read_b128 v[154:157], v165 offset:16384
	ds_read_b128 v[166:169], v165 offset:18432
	ds_read_b128 v[188:191], v165 offset:20480
	ds_read_b128 v[196:199], v165 offset:22528
	ds_read_b128 v[158:161], v165 offset:17408
	ds_read_b128 v[170:173], v165 offset:19456
	ds_read_b128 v[192:195], v165 offset:21504
	ds_read_b128 v[200:203], v165 offset:23552
	global_load_lds_dwordx4 v144, s[64:65]
	s_mov_b32 m0, s70
	s_nop 0
	global_load_lds_dwordx4 v146, s[64:65]
	s_barrier
	s_waitcnt lgkmcnt(7)
	v_mfma_f32_16x16x32_bf16 v[60:63], v[128:131], v[154:157], v[60:63]
	v_mfma_f32_16x16x32_bf16 v[56:59], v[136:139], v[154:157], v[56:59]
	s_waitcnt lgkmcnt(6)
	v_mfma_f32_16x16x32_bf16 v[44:47], v[128:131], v[166:169], v[44:47]
	v_mfma_f32_16x16x32_bf16 v[40:43], v[136:139], v[166:169], v[40:43]
	s_waitcnt lgkmcnt(5)
	v_mfma_f32_16x16x32_bf16 v[28:31], v[128:131], v[188:191], v[28:31]
	v_mfma_f32_16x16x32_bf16 v[24:27], v[136:139], v[188:191], v[24:27]
	s_waitcnt lgkmcnt(4)
	v_mfma_f32_16x16x32_bf16 v[12:15], v[128:131], v[196:199], v[12:15]
	v_mfma_f32_16x16x32_bf16 v[8:11], v[136:139], v[196:199], v[8:11]
	s_waitcnt lgkmcnt(3)
	v_mfma_f32_16x16x32_bf16 v[60:63], v[132:135], v[158:161], v[60:63]
	v_mfma_f32_16x16x32_bf16 v[56:59], v[140:143], v[158:161], v[56:59]
	s_waitcnt lgkmcnt(2)
	v_mfma_f32_16x16x32_bf16 v[44:47], v[132:135], v[170:173], v[44:47]
	v_mfma_f32_16x16x32_bf16 v[40:43], v[140:143], v[170:173], v[40:43]
	s_waitcnt lgkmcnt(1)
	v_mfma_f32_16x16x32_bf16 v[28:31], v[132:135], v[192:195], v[28:31]
	v_mfma_f32_16x16x32_bf16 v[24:27], v[140:143], v[192:195], v[24:27]
	s_waitcnt lgkmcnt(0)
	v_mfma_f32_16x16x32_bf16 v[12:15], v[132:135], v[200:203], v[12:15]
	v_mfma_f32_16x16x32_bf16 v[8:11], v[140:143], v[200:203], v[8:11]
	s_barrier
	s_add_u32 s18, s62, 0x18000
	s_addc_u32 s19, s63, 0
	s_add_i32 s28, s29, s68
	s_mov_b32 m0, s28
	s_nop 0
	global_load_lds_dwordx4 v176, s[18:19]
	s_add_i32 m0, s28, 0x2000
	s_nop 0
	global_load_lds_dwordx4 v148, s[18:19]
	s_waitcnt vmcnt(6)
	s_barrier
	v_mfma_f32_16x16x32_bf16 v[52:55], v[204:207], v[154:157], v[52:55]
	v_mfma_f32_16x16x32_bf16 v[48:51], v[212:215], v[154:157], v[48:51]
	v_mfma_f32_16x16x32_bf16 v[36:39], v[204:207], v[166:169], v[36:39]
	v_mfma_f32_16x16x32_bf16 v[32:35], v[212:215], v[166:169], v[32:35]
	v_mfma_f32_16x16x32_bf16 v[20:23], v[204:207], v[188:191], v[20:23]
	v_mfma_f32_16x16x32_bf16 v[16:19], v[212:215], v[188:191], v[16:19]
	v_mfma_f32_16x16x32_bf16 v[4:7], v[204:207], v[196:199], v[4:7]
	v_mfma_f32_16x16x32_bf16 v[0:3], v[212:215], v[196:199], v[0:3]
	v_mfma_f32_16x16x32_bf16 v[52:55], v[208:211], v[158:161], v[52:55]
	v_mfma_f32_16x16x32_bf16 v[48:51], v[232:235], v[158:161], v[48:51]
	v_mfma_f32_16x16x32_bf16 v[36:39], v[208:211], v[170:173], v[36:39]
	v_mfma_f32_16x16x32_bf16 v[32:35], v[232:235], v[170:173], v[32:35]
	v_mfma_f32_16x16x32_bf16 v[20:23], v[208:211], v[192:195], v[20:23]
	v_mfma_f32_16x16x32_bf16 v[16:19], v[232:235], v[192:195], v[16:19]
	v_mfma_f32_16x16x32_bf16 v[4:7], v[208:211], v[200:203], v[4:7]
	v_mfma_f32_16x16x32_bf16 v[0:3], v[232:235], v[200:203], v[0:3]
	s_add_i32 s28, 0, 0x18000
	s_barrier
	ds_read_b128 v[128:131], v174 offset:32768
	ds_read_b128 v[132:135], v174 offset:33792
	ds_read_b128 v[136:139], v174 offset:34816
	ds_read_b128 v[140:143], v174 offset:35840
	ds_read_b128 v[154:157], v165 offset:32768
	ds_read_b128 v[166:169], v165 offset:34816
	ds_read_b128 v[188:191], v165 offset:36864
	ds_read_b128 v[196:199], v165 offset:38912
	ds_read_b128 v[158:161], v165 offset:33792
	ds_read_b128 v[170:173], v165 offset:35840
	ds_read_b128 v[192:195], v165 offset:37888
	ds_read_b128 v[200:203], v165 offset:39936
	s_add_u32 s18, s64, 0x18000
	s_addc_u32 s19, s65, 0
	s_mov_b32 m0, s71
	s_nop 0
	global_load_lds_dwordx4 v144, s[18:19]
	s_mov_b32 m0, s72
	s_nop 0
	global_load_lds_dwordx4 v146, s[18:19]
	s_waitcnt lgkmcnt(8)
	s_barrier
	s_waitcnt lgkmcnt(7)
	v_mfma_f32_16x16x32_bf16 v[124:127], v[128:131], v[154:157], v[124:127]
	v_mfma_f32_16x16x32_bf16 v[120:123], v[136:139], v[154:157], v[120:123]
	s_waitcnt lgkmcnt(6)
	v_mfma_f32_16x16x32_bf16 v[108:111], v[128:131], v[166:169], v[108:111]
	v_mfma_f32_16x16x32_bf16 v[104:107], v[136:139], v[166:169], v[104:107]
	s_waitcnt lgkmcnt(5)
	v_mfma_f32_16x16x32_bf16 v[92:95], v[128:131], v[188:191], v[92:95]
	v_mfma_f32_16x16x32_bf16 v[88:91], v[136:139], v[188:191], v[88:91]
	s_waitcnt lgkmcnt(4)
	v_mfma_f32_16x16x32_bf16 v[76:79], v[128:131], v[196:199], v[76:79]
	v_mfma_f32_16x16x32_bf16 v[72:75], v[136:139], v[196:199], v[72:75]
	s_waitcnt lgkmcnt(3)
	v_mfma_f32_16x16x32_bf16 v[124:127], v[132:135], v[158:161], v[124:127]
	v_mfma_f32_16x16x32_bf16 v[120:123], v[140:143], v[158:161], v[120:123]
	s_waitcnt lgkmcnt(2)
	v_mfma_f32_16x16x32_bf16 v[108:111], v[132:135], v[170:173], v[108:111]
	v_mfma_f32_16x16x32_bf16 v[104:107], v[140:143], v[170:173], v[104:107]
	s_waitcnt lgkmcnt(1)
	v_mfma_f32_16x16x32_bf16 v[92:95], v[132:135], v[192:195], v[92:95]
	v_mfma_f32_16x16x32_bf16 v[88:91], v[140:143], v[192:195], v[88:91]
	s_waitcnt lgkmcnt(0)
	v_mfma_f32_16x16x32_bf16 v[76:79], v[132:135], v[200:203], v[76:79]
	v_mfma_f32_16x16x32_bf16 v[72:75], v[140:143], v[200:203], v[72:75]
	s_barrier
	ds_read_b128 v[204:207], v174 offset:49152
	ds_read_b128 v[208:211], v174 offset:50176
	ds_read_b128 v[212:215], v174 offset:51200
	ds_read_b128 v[232:235], v174 offset:52224
	s_add_i32 s29, 0, 0x1c000
	s_add_i32 s18, s28, s68
	s_add_i32 m0, s18, 0xffffff80
	s_nop 0
	global_load_lds_dwordx4 v176, s[62:63] offset:128
	s_add_i32 m0, s18, 0x1f80
	s_nop 0
	global_load_lds_dwordx4 v148, s[62:63] offset:128
	s_barrier
	s_waitcnt lgkmcnt(3)
	v_mfma_f32_16x16x32_bf16 v[116:119], v[204:207], v[154:157], v[116:119]
	s_waitcnt lgkmcnt(1)
	v_mfma_f32_16x16x32_bf16 v[112:115], v[212:215], v[154:157], v[112:115]
	v_mfma_f32_16x16x32_bf16 v[100:103], v[204:207], v[166:169], v[100:103]
	v_mfma_f32_16x16x32_bf16 v[96:99], v[212:215], v[166:169], v[96:99]
	v_mfma_f32_16x16x32_bf16 v[84:87], v[204:207], v[188:191], v[84:87]
	v_mfma_f32_16x16x32_bf16 v[80:83], v[212:215], v[188:191], v[80:83]
	v_mfma_f32_16x16x32_bf16 v[68:71], v[204:207], v[196:199], v[68:71]
	v_mfma_f32_16x16x32_bf16 v[64:67], v[212:215], v[196:199], v[64:67]
	v_mfma_f32_16x16x32_bf16 v[116:119], v[208:211], v[158:161], v[116:119]
	s_waitcnt lgkmcnt(0)
	v_mfma_f32_16x16x32_bf16 v[112:115], v[232:235], v[158:161], v[112:115]
	v_mfma_f32_16x16x32_bf16 v[100:103], v[208:211], v[170:173], v[100:103]
	v_mfma_f32_16x16x32_bf16 v[96:99], v[232:235], v[170:173], v[96:99]
	v_mfma_f32_16x16x32_bf16 v[84:87], v[208:211], v[192:195], v[84:87]
	v_mfma_f32_16x16x32_bf16 v[80:83], v[232:235], v[192:195], v[80:83]
	v_mfma_f32_16x16x32_bf16 v[68:71], v[208:211], v[200:203], v[68:71]
	v_mfma_f32_16x16x32_bf16 v[64:67], v[232:235], v[200:203], v[64:67]
	s_add_i32 m0, s75, 0xffffff80
	s_barrier
	ds_read_b128 v[154:157], v165 offset:49152
	ds_read_b128 v[166:169], v165 offset:51200
	ds_read_b128 v[188:191], v165 offset:53248
	ds_read_b128 v[196:199], v165 offset:55296
	ds_read_b128 v[158:161], v165 offset:50176
	ds_read_b128 v[170:173], v165 offset:52224
	ds_read_b128 v[192:195], v165 offset:54272
	ds_read_b128 v[200:203], v165 offset:56320
	global_load_lds_dwordx4 v144, s[64:65] offset:128
	s_add_i32 m0, s76, 0xffffff80
	s_nop 0
	global_load_lds_dwordx4 v146, s[64:65] offset:128
	s_barrier
	s_waitcnt lgkmcnt(7)
	v_mfma_f32_16x16x32_bf16 v[60:63], v[128:131], v[154:157], v[60:63]
	v_mfma_f32_16x16x32_bf16 v[56:59], v[136:139], v[154:157], v[56:59]
	s_waitcnt lgkmcnt(6)
	v_mfma_f32_16x16x32_bf16 v[44:47], v[128:131], v[166:169], v[44:47]
	v_mfma_f32_16x16x32_bf16 v[40:43], v[136:139], v[166:169], v[40:43]
	s_waitcnt lgkmcnt(5)
	v_mfma_f32_16x16x32_bf16 v[28:31], v[128:131], v[188:191], v[28:31]
	v_mfma_f32_16x16x32_bf16 v[24:27], v[136:139], v[188:191], v[24:27]
	s_waitcnt lgkmcnt(4)
	v_mfma_f32_16x16x32_bf16 v[12:15], v[128:131], v[196:199], v[12:15]
	v_mfma_f32_16x16x32_bf16 v[8:11], v[136:139], v[196:199], v[8:11]
	s_waitcnt lgkmcnt(3)
	v_mfma_f32_16x16x32_bf16 v[60:63], v[132:135], v[158:161], v[60:63]
	v_mfma_f32_16x16x32_bf16 v[56:59], v[140:143], v[158:161], v[56:59]
	s_waitcnt lgkmcnt(2)
	v_mfma_f32_16x16x32_bf16 v[44:47], v[132:135], v[170:173], v[44:47]
	v_mfma_f32_16x16x32_bf16 v[40:43], v[140:143], v[170:173], v[40:43]
	s_waitcnt lgkmcnt(1)
	v_mfma_f32_16x16x32_bf16 v[28:31], v[132:135], v[192:195], v[28:31]
	v_mfma_f32_16x16x32_bf16 v[24:27], v[140:143], v[192:195], v[24:27]
	s_waitcnt lgkmcnt(0)
	v_mfma_f32_16x16x32_bf16 v[12:15], v[132:135], v[200:203], v[12:15]
	v_mfma_f32_16x16x32_bf16 v[8:11], v[140:143], v[200:203], v[8:11]
	s_barrier
	s_add_u32 s18, s62, 0x18080
	s_addc_u32 s19, s63, 0
	s_add_i32 s28, s29, s68
	s_mov_b32 m0, s28
	s_nop 0
	global_load_lds_dwordx4 v176, s[18:19]
	s_add_i32 m0, s28, 0x2000
	s_nop 0
	global_load_lds_dwordx4 v148, s[18:19]
	s_waitcnt vmcnt(6)
	s_barrier
	v_mfma_f32_16x16x32_bf16 v[52:55], v[204:207], v[154:157], v[52:55]
	v_mfma_f32_16x16x32_bf16 v[48:51], v[212:215], v[154:157], v[48:51]
	v_mfma_f32_16x16x32_bf16 v[36:39], v[204:207], v[166:169], v[36:39]
	v_mfma_f32_16x16x32_bf16 v[32:35], v[212:215], v[166:169], v[32:35]
	v_mfma_f32_16x16x32_bf16 v[20:23], v[204:207], v[188:191], v[20:23]
	v_mfma_f32_16x16x32_bf16 v[16:19], v[212:215], v[188:191], v[16:19]
	v_mfma_f32_16x16x32_bf16 v[4:7], v[204:207], v[196:199], v[4:7]
	v_mfma_f32_16x16x32_bf16 v[0:3], v[212:215], v[196:199], v[0:3]
	v_mfma_f32_16x16x32_bf16 v[52:55], v[208:211], v[158:161], v[52:55]
	v_mfma_f32_16x16x32_bf16 v[48:51], v[232:235], v[158:161], v[48:51]
	v_mfma_f32_16x16x32_bf16 v[36:39], v[208:211], v[170:173], v[36:39]
	v_mfma_f32_16x16x32_bf16 v[32:35], v[232:235], v[170:173], v[32:35]
	v_mfma_f32_16x16x32_bf16 v[20:23], v[208:211], v[192:195], v[20:23]
	v_mfma_f32_16x16x32_bf16 v[16:19], v[232:235], v[192:195], v[16:19]
	v_mfma_f32_16x16x32_bf16 v[4:7], v[208:211], v[200:203], v[4:7]
	v_mfma_f32_16x16x32_bf16 v[0:3], v[232:235], v[200:203], v[0:3]
	s_add_u32 s85, s85, 0x100
	s_addc_u32 s91, s91, 0
	s_cmp_lt_i32 vcc_lo, s67
	s_mov_b64 s[18:19], s[4:5]
	s_mov_b32 s62, vcc_lo
	s_barrier
	s_cbranch_scc1 .LBB0_413
	s_ashr_i32 s4, s66, 2
	v_mov_b32_e32 v128, v163
	v_mov_b32_e32 v166, v162
	s_cmp_eq_u32 s4, 2
	s_cbranch_scc1 .LBB0_416
	s_mul_i32 s13, s4, 0x2280000
	s_mul_hi_i32 s5, s4, 0x2280000
	s_add_u32 s18, s13, 0x5858000
	s_addc_u32 s19, s5, 0
	s_mov_b32 s62, 1.0
	s_branch .LBB0_417

.LBB0_505:
	ds_read_b128 v[138:141], v174
	ds_read_b128 v[146:149], v174 offset:1024
	ds_read_b128 v[150:153], v174 offset:2048
	ds_read_b128 v[154:157], v174 offset:3072
	ds_read_b128 v[158:161], v145
	ds_read_b128 v[166:169], v145 offset:2048
	ds_read_b128 v[188:191], v145 offset:4096
	ds_read_b128 v[196:199], v145 offset:6144
	ds_read_b128 v[162:165], v145 offset:1024
	ds_read_b128 v[170:173], v145 offset:3072
	ds_read_b128 v[192:195], v145 offset:5120
	ds_read_b128 v[200:203], v145 offset:7168
	s_add_u32 s6, s4, 0xfff80080
	s_addc_u32 s7, s5, -1
	s_add_i32 s28, 0, 0x10000
	s_cmp_eq_u32 s72, 28
	s_cselect_b32 s9, s10, s7
	s_cselect_b32 s8, s11, s6
	s_cselect_b32 s7, s63, s71
	s_cselect_b32 s6, s65, s70
	s_add_i32 m0, s17, 0xc000
	s_nop 0
	global_load_lds_dwordx4 v134, s[4:5]
	s_add_i32 m0, s17, 0xe000
	s_nop 0
	global_load_lds_dwordx4 v136, s[4:5]
	s_waitcnt lgkmcnt(8)
	s_barrier
	s_waitcnt lgkmcnt(7)
	v_mfma_f32_16x16x32_bf16 v[124:127], v[138:141], v[158:161], v[124:127]
	v_mfma_f32_16x16x32_bf16 v[120:123], v[150:153], v[158:161], v[120:123]
	s_waitcnt lgkmcnt(6)
	v_mfma_f32_16x16x32_bf16 v[116:119], v[138:141], v[166:169], v[116:119]
	v_mfma_f32_16x16x32_bf16 v[108:111], v[150:153], v[166:169], v[108:111]
	s_waitcnt lgkmcnt(5)
	v_mfma_f32_16x16x32_bf16 v[100:103], v[138:141], v[188:191], v[100:103]
	v_mfma_f32_16x16x32_bf16 v[92:95], v[150:153], v[188:191], v[92:95]
	s_waitcnt lgkmcnt(4)
	v_mfma_f32_16x16x32_bf16 v[84:87], v[138:141], v[196:199], v[84:87]
	v_mfma_f32_16x16x32_bf16 v[76:79], v[150:153], v[196:199], v[76:79]
	s_waitcnt lgkmcnt(3)
	v_mfma_f32_16x16x32_bf16 v[124:127], v[146:149], v[162:165], v[124:127]
	v_mfma_f32_16x16x32_bf16 v[120:123], v[154:157], v[162:165], v[120:123]
	s_waitcnt lgkmcnt(2)
	v_mfma_f32_16x16x32_bf16 v[116:119], v[146:149], v[170:173], v[116:119]
	v_mfma_f32_16x16x32_bf16 v[108:111], v[154:157], v[170:173], v[108:111]
	s_waitcnt lgkmcnt(1)
	v_mfma_f32_16x16x32_bf16 v[100:103], v[146:149], v[192:195], v[100:103]
	v_mfma_f32_16x16x32_bf16 v[92:95], v[154:157], v[192:195], v[92:95]
	s_waitcnt lgkmcnt(0)
	v_mfma_f32_16x16x32_bf16 v[84:87], v[146:149], v[200:203], v[84:87]
	v_mfma_f32_16x16x32_bf16 v[76:79], v[154:157], v[200:203], v[76:79]
	s_barrier
	ds_read_b128 v[204:207], v174 offset:16384
	ds_read_b128 v[208:211], v174 offset:17408
	ds_read_b128 v[212:215], v174 offset:18432
	ds_read_b128 v[232:235], v174 offset:19456
	s_add_i32 s29, 0, 0x14000
	s_add_i32 s28, s28, s77
	s_mov_b32 m0, s28
	s_nop 0
	global_load_lds_dwordx4 v176, s[6:7]
	s_add_i32 m0, s28, 0x2000
	s_nop 0
	global_load_lds_dwordx4 v132, s[6:7]
	s_barrier
	s_waitcnt lgkmcnt(3)
	v_mfma_f32_16x16x32_bf16 v[112:115], v[204:207], v[158:161], v[112:115]
	s_waitcnt lgkmcnt(1)
	v_mfma_f32_16x16x32_bf16 v[104:107], v[212:215], v[158:161], v[104:107]
	v_mfma_f32_16x16x32_bf16 v[96:99], v[204:207], v[166:169], v[96:99]
	v_mfma_f32_16x16x32_bf16 v[88:91], v[212:215], v[166:169], v[88:91]
	v_mfma_f32_16x16x32_bf16 v[80:83], v[204:207], v[188:191], v[80:83]
	v_mfma_f32_16x16x32_bf16 v[72:75], v[212:215], v[188:191], v[72:75]
	v_mfma_f32_16x16x32_bf16 v[68:71], v[204:207], v[196:199], v[68:71]
	v_mfma_f32_16x16x32_bf16 v[64:67], v[212:215], v[196:199], v[64:67]
	v_mfma_f32_16x16x32_bf16 v[112:115], v[208:211], v[162:165], v[112:115]
	s_waitcnt lgkmcnt(0)
	v_mfma_f32_16x16x32_bf16 v[104:107], v[232:235], v[162:165], v[104:107]
	v_mfma_f32_16x16x32_bf16 v[96:99], v[208:211], v[170:173], v[96:99]
	v_mfma_f32_16x16x32_bf16 v[88:91], v[232:235], v[170:173], v[88:91]
	v_mfma_f32_16x16x32_bf16 v[80:83], v[208:211], v[192:195], v[80:83]
	v_mfma_f32_16x16x32_bf16 v[72:75], v[232:235], v[192:195], v[72:75]
	v_mfma_f32_16x16x32_bf16 v[68:71], v[208:211], v[200:203], v[68:71]
	v_mfma_f32_16x16x32_bf16 v[64:67], v[232:235], v[200:203], v[64:67]
	s_mov_b32 m0, s17
	s_barrier
	ds_read_b128 v[158:161], v145 offset:16384
	ds_read_b128 v[166:169], v145 offset:18432
	ds_read_b128 v[188:191], v145 offset:20480
	ds_read_b128 v[196:199], v145 offset:22528
	ds_read_b128 v[162:165], v145 offset:17408
	ds_read_b128 v[170:173], v145 offset:19456
	ds_read_b128 v[192:195], v145 offset:21504
	ds_read_b128 v[200:203], v145 offset:23552
	global_load_lds_dwordx4 v128, s[8:9]
	s_mov_b32 m0, s19
	s_nop 0
	global_load_lds_dwordx4 v130, s[8:9]
	s_barrier
	s_waitcnt lgkmcnt(7)
	v_mfma_f32_16x16x32_bf16 v[60:63], v[138:141], v[158:161], v[60:63]
	v_mfma_f32_16x16x32_bf16 v[56:59], v[150:153], v[158:161], v[56:59]
	s_waitcnt lgkmcnt(6)
	v_mfma_f32_16x16x32_bf16 v[52:55], v[138:141], v[166:169], v[52:55]
	v_mfma_f32_16x16x32_bf16 v[44:47], v[150:153], v[166:169], v[44:47]
	s_waitcnt lgkmcnt(5)
	v_mfma_f32_16x16x32_bf16 v[36:39], v[138:141], v[188:191], v[36:39]
	v_mfma_f32_16x16x32_bf16 v[28:31], v[150:153], v[188:191], v[28:31]
	s_waitcnt lgkmcnt(4)
	v_mfma_f32_16x16x32_bf16 v[20:23], v[138:141], v[196:199], v[20:23]
	v_mfma_f32_16x16x32_bf16 v[12:15], v[150:153], v[196:199], v[12:15]
	s_waitcnt lgkmcnt(3)
	v_mfma_f32_16x16x32_bf16 v[60:63], v[146:149], v[162:165], v[60:63]
	v_mfma_f32_16x16x32_bf16 v[56:59], v[154:157], v[162:165], v[56:59]
	s_waitcnt lgkmcnt(2)
	v_mfma_f32_16x16x32_bf16 v[52:55], v[146:149], v[170:173], v[52:55]
	v_mfma_f32_16x16x32_bf16 v[44:47], v[154:157], v[170:173], v[44:47]
	s_waitcnt lgkmcnt(1)
	v_mfma_f32_16x16x32_bf16 v[36:39], v[146:149], v[192:195], v[36:39]
	v_mfma_f32_16x16x32_bf16 v[28:31], v[154:157], v[192:195], v[28:31]
	s_waitcnt lgkmcnt(0)
	v_mfma_f32_16x16x32_bf16 v[20:23], v[146:149], v[200:203], v[20:23]
	v_mfma_f32_16x16x32_bf16 v[12:15], v[154:157], v[200:203], v[12:15]
	s_barrier
	s_add_u32 vcc_lo, s6, 0x80000
	s_addc_u32 vcc_hi, s7, 0
	s_add_i32 s28, s29, s77
	s_mov_b32 m0, s28
	s_nop 0
	global_load_lds_dwordx4 v176, vcc
	s_add_i32 m0, s28, 0x2000
	s_nop 0
	global_load_lds_dwordx4 v132, vcc
	s_waitcnt vmcnt(6)
	s_barrier
	v_mfma_f32_16x16x32_bf16 v[48:51], v[204:207], v[158:161], v[48:51]
	v_mfma_f32_16x16x32_bf16 v[40:43], v[212:215], v[158:161], v[40:43]
	v_mfma_f32_16x16x32_bf16 v[32:35], v[204:207], v[166:169], v[32:35]
	v_mfma_f32_16x16x32_bf16 v[24:27], v[212:215], v[166:169], v[24:27]
	v_mfma_f32_16x16x32_bf16 v[16:19], v[204:207], v[188:191], v[16:19]
	v_mfma_f32_16x16x32_bf16 v[8:11], v[212:215], v[188:191], v[8:11]
	v_mfma_f32_16x16x32_bf16 v[4:7], v[204:207], v[196:199], v[4:7]
	v_mfma_f32_16x16x32_bf16 v[0:3], v[212:215], v[196:199], v[0:3]
	v_mfma_f32_16x16x32_bf16 v[48:51], v[208:211], v[162:165], v[48:51]
	v_mfma_f32_16x16x32_bf16 v[40:43], v[232:235], v[162:165], v[40:43]
	v_mfma_f32_16x16x32_bf16 v[32:35], v[208:211], v[170:173], v[32:35]
	v_mfma_f32_16x16x32_bf16 v[24:27], v[232:235], v[170:173], v[24:27]
	v_mfma_f32_16x16x32_bf16 v[16:19], v[208:211], v[192:195], v[16:19]
	v_mfma_f32_16x16x32_bf16 v[8:11], v[232:235], v[192:195], v[8:11]
	v_mfma_f32_16x16x32_bf16 v[4:7], v[208:211], v[200:203], v[4:7]
	v_mfma_f32_16x16x32_bf16 v[0:3], v[232:235], v[200:203], v[0:3]
	s_add_i32 s28, 0, 0x18000
	s_barrier
	ds_read_b128 v[138:141], v174 offset:32768
	ds_read_b128 v[146:149], v174 offset:33792
	ds_read_b128 v[150:153], v174 offset:34816
	ds_read_b128 v[154:157], v174 offset:35840
	ds_read_b128 v[158:161], v145 offset:32768
	ds_read_b128 v[166:169], v145 offset:34816
	ds_read_b128 v[188:191], v145 offset:36864
	ds_read_b128 v[196:199], v145 offset:38912
	ds_read_b128 v[162:165], v145 offset:33792
	ds_read_b128 v[170:173], v145 offset:35840
	ds_read_b128 v[192:195], v145 offset:37888
	ds_read_b128 v[200:203], v145 offset:39936
	s_add_u32 s98, s8, 0x80000
	s_addc_u32 s99, s9, 0
	s_mov_b32 m0, s78
	s_nop 0
	global_load_lds_dwordx4 v128, s[98:99]
	s_mov_b32 m0, s79
	s_nop 0
	global_load_lds_dwordx4 v130, s[98:99]
	s_waitcnt lgkmcnt(8)
	s_barrier
	s_waitcnt lgkmcnt(7)
	v_mfma_f32_16x16x32_bf16 v[124:127], v[138:141], v[158:161], v[124:127]
	v_mfma_f32_16x16x32_bf16 v[120:123], v[150:153], v[158:161], v[120:123]
	s_waitcnt lgkmcnt(6)
	v_mfma_f32_16x16x32_bf16 v[116:119], v[138:141], v[166:169], v[116:119]
	v_mfma_f32_16x16x32_bf16 v[108:111], v[150:153], v[166:169], v[108:111]
	s_waitcnt lgkmcnt(5)
	v_mfma_f32_16x16x32_bf16 v[100:103], v[138:141], v[188:191], v[100:103]
	v_mfma_f32_16x16x32_bf16 v[92:95], v[150:153], v[188:191], v[92:95]
	s_waitcnt lgkmcnt(4)
	v_mfma_f32_16x16x32_bf16 v[84:87], v[138:141], v[196:199], v[84:87]
	v_mfma_f32_16x16x32_bf16 v[76:79], v[150:153], v[196:199], v[76:79]
	s_waitcnt lgkmcnt(3)
	v_mfma_f32_16x16x32_bf16 v[124:127], v[146:149], v[162:165], v[124:127]
	v_mfma_f32_16x16x32_bf16 v[120:123], v[154:157], v[162:165], v[120:123]
	s_waitcnt lgkmcnt(2)
	v_mfma_f32_16x16x32_bf16 v[116:119], v[146:149], v[170:173], v[116:119]
	v_mfma_f32_16x16x32_bf16 v[108:111], v[154:157], v[170:173], v[108:111]
	s_waitcnt lgkmcnt(1)
	v_mfma_f32_16x16x32_bf16 v[100:103], v[146:149], v[192:195], v[100:103]
	v_mfma_f32_16x16x32_bf16 v[92:95], v[154:157], v[192:195], v[92:95]
	s_waitcnt lgkmcnt(0)
	v_mfma_f32_16x16x32_bf16 v[84:87], v[146:149], v[200:203], v[84:87]
	v_mfma_f32_16x16x32_bf16 v[76:79], v[154:157], v[200:203], v[76:79]
	s_barrier
	ds_read_b128 v[204:207], v174 offset:49152
	ds_read_b128 v[208:211], v174 offset:50176
	ds_read_b128 v[212:215], v174 offset:51200
	ds_read_b128 v[232:235], v174 offset:52224
	s_add_i32 s100, 0, 0x1c000
	s_add_i32 s101, s28, s77
	s_add_i32 m0, s101, 0xffffff80
	s_nop 0
	global_load_lds_dwordx4 v176, s[6:7] offset:128
	s_add_i32 m0, s101, 0x1f80
	s_nop 0
	global_load_lds_dwordx4 v132, s[6:7] offset:128
	s_barrier
	s_waitcnt lgkmcnt(3)
	v_mfma_f32_16x16x32_bf16 v[112:115], v[204:207], v[158:161], v[112:115]
	s_waitcnt lgkmcnt(1)
	v_mfma_f32_16x16x32_bf16 v[104:107], v[212:215], v[158:161], v[104:107]
	v_mfma_f32_16x16x32_bf16 v[96:99], v[204:207], v[166:169], v[96:99]
	v_mfma_f32_16x16x32_bf16 v[88:91], v[212:215], v[166:169], v[88:91]
	v_mfma_f32_16x16x32_bf16 v[80:83], v[204:207], v[188:191], v[80:83]
	v_mfma_f32_16x16x32_bf16 v[72:75], v[212:215], v[188:191], v[72:75]
	v_mfma_f32_16x16x32_bf16 v[68:71], v[204:207], v[196:199], v[68:71]
	v_mfma_f32_16x16x32_bf16 v[64:67], v[212:215], v[196:199], v[64:67]
	v_mfma_f32_16x16x32_bf16 v[112:115], v[208:211], v[162:165], v[112:115]
	s_waitcnt lgkmcnt(0)
	v_mfma_f32_16x16x32_bf16 v[104:107], v[232:235], v[162:165], v[104:107]
	v_mfma_f32_16x16x32_bf16 v[96:99], v[208:211], v[170:173], v[96:99]
	v_mfma_f32_16x16x32_bf16 v[88:91], v[232:235], v[170:173], v[88:91]
	v_mfma_f32_16x16x32_bf16 v[80:83], v[208:211], v[192:195], v[80:83]
	v_mfma_f32_16x16x32_bf16 v[72:75], v[232:235], v[192:195], v[72:75]
	v_mfma_f32_16x16x32_bf16 v[68:71], v[208:211], v[200:203], v[68:71]
	v_mfma_f32_16x16x32_bf16 v[64:67], v[232:235], v[200:203], v[64:67]
	s_add_i32 m0, s82, 0xffffff80
	s_barrier
	ds_read_b128 v[158:161], v145 offset:49152
	ds_read_b128 v[166:169], v145 offset:51200
	ds_read_b128 v[188:191], v145 offset:53248
	ds_read_b128 v[196:199], v145 offset:55296
	ds_read_b128 v[162:165], v145 offset:50176
	ds_read_b128 v[170:173], v145 offset:52224
	ds_read_b128 v[192:195], v145 offset:54272
	ds_read_b128 v[200:203], v145 offset:56320
	global_load_lds_dwordx4 v128, s[8:9] offset:128
	s_add_i32 m0, s83, 0xffffff80
	s_nop 0
	global_load_lds_dwordx4 v130, s[8:9] offset:128
	s_barrier
	s_waitcnt lgkmcnt(7)
	v_mfma_f32_16x16x32_bf16 v[60:63], v[138:141], v[158:161], v[60:63]
	v_mfma_f32_16x16x32_bf16 v[56:59], v[150:153], v[158:161], v[56:59]
	s_waitcnt lgkmcnt(6)
	v_mfma_f32_16x16x32_bf16 v[52:55], v[138:141], v[166:169], v[52:55]
	v_mfma_f32_16x16x32_bf16 v[44:47], v[150:153], v[166:169], v[44:47]
	s_waitcnt lgkmcnt(5)
	v_mfma_f32_16x16x32_bf16 v[36:39], v[138:141], v[188:191], v[36:39]
	v_mfma_f32_16x16x32_bf16 v[28:31], v[150:153], v[188:191], v[28:31]
	s_waitcnt lgkmcnt(4)
	v_mfma_f32_16x16x32_bf16 v[20:23], v[138:141], v[196:199], v[20:23]
	v_mfma_f32_16x16x32_bf16 v[12:15], v[150:153], v[196:199], v[12:15]
	s_waitcnt lgkmcnt(3)
	v_mfma_f32_16x16x32_bf16 v[60:63], v[146:149], v[162:165], v[60:63]
	v_mfma_f32_16x16x32_bf16 v[56:59], v[154:157], v[162:165], v[56:59]
	s_waitcnt lgkmcnt(2)
	v_mfma_f32_16x16x32_bf16 v[52:55], v[146:149], v[170:173], v[52:55]
	v_mfma_f32_16x16x32_bf16 v[44:47], v[154:157], v[170:173], v[44:47]
	s_waitcnt lgkmcnt(1)
	v_mfma_f32_16x16x32_bf16 v[36:39], v[146:149], v[192:195], v[36:39]
	v_mfma_f32_16x16x32_bf16 v[28:31], v[154:157], v[192:195], v[28:31]
	s_waitcnt lgkmcnt(0)
	v_mfma_f32_16x16x32_bf16 v[20:23], v[146:149], v[200:203], v[20:23]
	v_mfma_f32_16x16x32_bf16 v[12:15], v[154:157], v[200:203], v[12:15]
	s_barrier
	s_add_u32 s6, s6, 0x80080
	s_addc_u32 s7, s7, 0
	s_add_i32 s100, s100, s77
	s_mov_b32 m0, s100
	s_nop 0
	global_load_lds_dwordx4 v176, s[6:7]
	s_add_i32 m0, s100, 0x2000
	s_nop 0
	global_load_lds_dwordx4 v132, s[6:7]
	s_waitcnt vmcnt(6)
	s_barrier
	v_mfma_f32_16x16x32_bf16 v[48:51], v[204:207], v[158:161], v[48:51]
	v_mfma_f32_16x16x32_bf16 v[40:43], v[212:215], v[158:161], v[40:43]
	v_mfma_f32_16x16x32_bf16 v[32:35], v[204:207], v[166:169], v[32:35]
	v_mfma_f32_16x16x32_bf16 v[24:27], v[212:215], v[166:169], v[24:27]
	v_mfma_f32_16x16x32_bf16 v[16:19], v[204:207], v[188:191], v[16:19]
	v_mfma_f32_16x16x32_bf16 v[8:11], v[212:215], v[188:191], v[8:11]
	v_mfma_f32_16x16x32_bf16 v[4:7], v[204:207], v[196:199], v[4:7]
	v_mfma_f32_16x16x32_bf16 v[0:3], v[212:215], v[196:199], v[0:3]
	v_mfma_f32_16x16x32_bf16 v[48:51], v[208:211], v[162:165], v[48:51]
	v_mfma_f32_16x16x32_bf16 v[40:43], v[232:235], v[162:165], v[40:43]
	v_mfma_f32_16x16x32_bf16 v[32:35], v[208:211], v[170:173], v[32:35]
	v_mfma_f32_16x16x32_bf16 v[24:27], v[232:235], v[170:173], v[24:27]
	v_mfma_f32_16x16x32_bf16 v[16:19], v[208:211], v[192:195], v[16:19]
	v_mfma_f32_16x16x32_bf16 v[8:11], v[232:235], v[192:195], v[8:11]
	v_mfma_f32_16x16x32_bf16 v[4:7], v[208:211], v[200:203], v[4:7]
	v_mfma_f32_16x16x32_bf16 v[0:3], v[232:235], v[200:203], v[0:3]
	s_add_i32 s72, s72, 2
	s_add_u32 s4, s4, 0x100
	s_addc_u32 s5, s5, 0
	s_add_u32 s70, s70, 0x100
	s_addc_u32 s71, s71, 0
	s_cmp_lt_u32 s72, 30
	s_barrier
	s_cbranch_scc1 .LBB0_505
	v_mov_b32_e32 v147, v142
	v_mov_b32_e32 v146, v143
	s_cmp_lt_i32 s16, 12
	s_mov_b64 s[4:5], -1
	s_cbranch_scc1 .LBB0_1052
	s_lshl_b32 s4, s18, 8
	s_add_i32 s4, s4, s80
	v_add_u32_e32 v149, s4, v147
	s_lshl_b32 s4, s16, 8
	s_add_i32 s4, s84, s4
	v_lshl_add_u32 v138, v146, 3, s4
	v_mad_i64_i32 v[140:141], s[4:5], v149, s97, 0
	v_cmp_gt_i32_e32 vcc, s34, v138
	s_and_saveexec_b64 s[10:11], vcc
	s_cbranch_execz .LBB0_541
	v_cmp_lt_i32_e64 s[8:9], 63, v138
	v_cmp_gt_u32_e64 s[4:5], s93, v138
	v_cmp_gt_u32_e64 s[6:7], s96, v138
	s_and_saveexec_b64 s[70:71], s[8:9]
	s_xor_b64 s[70:71], exec, s[70:71]
	s_cbranch_execz .LBB0_510
	v_mul_f32_e32 v139, 0xbfb8aa3b, v124
	v_exp_f32_e32 v139, v139
	s_nop 0
	v_add_f32_e32 v139, 1.0, v139
	v_rcp_f32_e32 v139, v139
	s_nop 0
	v_cndmask_b32_e64 v139, 0, v139, s[6:7]
	v_cndmask_b32_e64 v139, v139, v124, s[4:5]
	s_andn2_saveexec_b64 s[70:71], s[70:71]
	s_cbranch_execz .LBB0_512
	s_branch .LBB0_511

.LBB0_1114:
	ds_read_b128 v[128:131], v174
	ds_read_b128 v[132:135], v174 offset:1024
	ds_read_b128 v[136:139], v174 offset:2048
	ds_read_b128 v[140:143], v174 offset:3072
	ds_read_b128 v[144:147], v195
	ds_read_b128 v[162:165], v195 offset:2048
	ds_read_b128 v[170:173], v195 offset:4096
	ds_read_b128 v[196:199], v195 offset:6144
	ds_read_b128 v[148:151], v195 offset:1024
	ds_read_b128 v[166:169], v195 offset:3072
	ds_read_b128 v[188:191], v195 offset:5120
	ds_read_b128 v[200:203], v195 offset:7168
	s_add_i32 vcc_hi, s66, 2
	s_add_u32 s28, s64, 0x80
	s_addc_u32 s29, s65, 0
	s_add_i32 s88, 0, 0x10000
	s_cmp_eq_u32 s85, s66
	s_cselect_b32 s66, s4, s28
	s_cselect_b32 s67, s5, s29
	s_cselect_b32 s69, s7, vcc_lo
	s_cselect_b32 s68, s6, s91
	s_add_i32 m0, s70, 0xc000
	s_nop 0
	global_load_lds_dwordx4 v158, s[64:65]
	s_add_i32 m0, s70, 0xe000
	s_nop 0
	global_load_lds_dwordx4 v160, s[64:65]
	s_waitcnt lgkmcnt(8)
	s_barrier
	s_waitcnt lgkmcnt(7)
	v_mfma_f32_16x16x32_bf16 v[124:127], v[128:131], v[144:147], v[124:127]
	v_mfma_f32_16x16x32_bf16 v[120:123], v[136:139], v[144:147], v[120:123]
	s_waitcnt lgkmcnt(6)
	v_mfma_f32_16x16x32_bf16 v[108:111], v[128:131], v[162:165], v[108:111]
	v_mfma_f32_16x16x32_bf16 v[104:107], v[136:139], v[162:165], v[104:107]
	s_waitcnt lgkmcnt(5)
	v_mfma_f32_16x16x32_bf16 v[92:95], v[128:131], v[170:173], v[92:95]
	v_mfma_f32_16x16x32_bf16 v[88:91], v[136:139], v[170:173], v[88:91]
	s_waitcnt lgkmcnt(4)
	v_mfma_f32_16x16x32_bf16 v[76:79], v[128:131], v[196:199], v[76:79]
	v_mfma_f32_16x16x32_bf16 v[72:75], v[136:139], v[196:199], v[72:75]
	s_waitcnt lgkmcnt(3)
	v_mfma_f32_16x16x32_bf16 v[124:127], v[132:135], v[148:151], v[124:127]
	v_mfma_f32_16x16x32_bf16 v[120:123], v[140:143], v[148:151], v[120:123]
	s_waitcnt lgkmcnt(2)
	v_mfma_f32_16x16x32_bf16 v[108:111], v[132:135], v[166:169], v[108:111]
	v_mfma_f32_16x16x32_bf16 v[104:107], v[140:143], v[166:169], v[104:107]
	s_waitcnt lgkmcnt(1)
	v_mfma_f32_16x16x32_bf16 v[92:95], v[132:135], v[188:191], v[92:95]
	v_mfma_f32_16x16x32_bf16 v[88:91], v[140:143], v[188:191], v[88:91]
	s_waitcnt lgkmcnt(0)
	v_mfma_f32_16x16x32_bf16 v[76:79], v[132:135], v[200:203], v[76:79]
	v_mfma_f32_16x16x32_bf16 v[72:75], v[140:143], v[200:203], v[72:75]
	s_barrier
	ds_read_b128 v[204:207], v174 offset:16384
	ds_read_b128 v[208:211], v174 offset:17408
	ds_read_b128 v[212:215], v174 offset:18432
	ds_read_b128 v[232:235], v174 offset:19456
	s_add_i32 s28, 0, 0x14000
	s_add_i32 s29, s88, s47
	s_mov_b32 m0, s29
	s_nop 0
	global_load_lds_dwordx4 v176, s[68:69]
	s_add_i32 m0, s29, 0x2000
	s_nop 0
	global_load_lds_dwordx4 v156, s[68:69]
	s_barrier
	s_waitcnt lgkmcnt(3)
	v_mfma_f32_16x16x32_bf16 v[116:119], v[204:207], v[144:147], v[116:119]
	s_waitcnt lgkmcnt(1)
	v_mfma_f32_16x16x32_bf16 v[112:115], v[212:215], v[144:147], v[112:115]
	v_mfma_f32_16x16x32_bf16 v[100:103], v[204:207], v[162:165], v[100:103]
	v_mfma_f32_16x16x32_bf16 v[96:99], v[212:215], v[162:165], v[96:99]
	v_mfma_f32_16x16x32_bf16 v[84:87], v[204:207], v[170:173], v[84:87]
	v_mfma_f32_16x16x32_bf16 v[80:83], v[212:215], v[170:173], v[80:83]
	v_mfma_f32_16x16x32_bf16 v[68:71], v[204:207], v[196:199], v[68:71]
	v_mfma_f32_16x16x32_bf16 v[64:67], v[212:215], v[196:199], v[64:67]
	v_mfma_f32_16x16x32_bf16 v[116:119], v[208:211], v[148:151], v[116:119]
	s_waitcnt lgkmcnt(0)
	v_mfma_f32_16x16x32_bf16 v[112:115], v[232:235], v[148:151], v[112:115]
	v_mfma_f32_16x16x32_bf16 v[100:103], v[208:211], v[166:169], v[100:103]
	v_mfma_f32_16x16x32_bf16 v[96:99], v[232:235], v[166:169], v[96:99]
	v_mfma_f32_16x16x32_bf16 v[84:87], v[208:211], v[188:191], v[84:87]
	v_mfma_f32_16x16x32_bf16 v[80:83], v[232:235], v[188:191], v[80:83]
	v_mfma_f32_16x16x32_bf16 v[68:71], v[208:211], v[200:203], v[68:71]
	v_mfma_f32_16x16x32_bf16 v[64:67], v[232:235], v[200:203], v[64:67]
	s_mov_b32 m0, s70
	s_barrier
	ds_read_b128 v[144:147], v195 offset:16384
	ds_read_b128 v[162:165], v195 offset:18432
	ds_read_b128 v[170:173], v195 offset:20480
	ds_read_b128 v[196:199], v195 offset:22528
	ds_read_b128 v[148:151], v195 offset:17408
	ds_read_b128 v[166:169], v195 offset:19456
	ds_read_b128 v[188:191], v195 offset:21504
	ds_read_b128 v[200:203], v195 offset:23552
	global_load_lds_dwordx4 v152, s[66:67]
	s_mov_b32 m0, s71
	s_nop 0
	global_load_lds_dwordx4 v154, s[66:67]
	s_barrier
	s_waitcnt lgkmcnt(7)
	v_mfma_f32_16x16x32_bf16 v[60:63], v[128:131], v[144:147], v[60:63]
	v_mfma_f32_16x16x32_bf16 v[56:59], v[136:139], v[144:147], v[56:59]
	s_waitcnt lgkmcnt(6)
	v_mfma_f32_16x16x32_bf16 v[44:47], v[128:131], v[162:165], v[44:47]
	v_mfma_f32_16x16x32_bf16 v[40:43], v[136:139], v[162:165], v[40:43]
	s_waitcnt lgkmcnt(5)
	v_mfma_f32_16x16x32_bf16 v[28:31], v[128:131], v[170:173], v[28:31]
	v_mfma_f32_16x16x32_bf16 v[24:27], v[136:139], v[170:173], v[24:27]
	s_waitcnt lgkmcnt(4)
	v_mfma_f32_16x16x32_bf16 v[12:15], v[128:131], v[196:199], v[12:15]
	v_mfma_f32_16x16x32_bf16 v[8:11], v[136:139], v[196:199], v[8:11]
	s_waitcnt lgkmcnt(3)
	v_mfma_f32_16x16x32_bf16 v[60:63], v[132:135], v[148:151], v[60:63]
	v_mfma_f32_16x16x32_bf16 v[56:59], v[140:143], v[148:151], v[56:59]
	s_waitcnt lgkmcnt(2)
	v_mfma_f32_16x16x32_bf16 v[44:47], v[132:135], v[166:169], v[44:47]
	v_mfma_f32_16x16x32_bf16 v[40:43], v[140:143], v[166:169], v[40:43]
	s_waitcnt lgkmcnt(1)
	v_mfma_f32_16x16x32_bf16 v[28:31], v[132:135], v[188:191], v[28:31]
	v_mfma_f32_16x16x32_bf16 v[24:27], v[140:143], v[188:191], v[24:27]
	s_waitcnt lgkmcnt(0)
	v_mfma_f32_16x16x32_bf16 v[12:15], v[132:135], v[200:203], v[12:15]
	v_mfma_f32_16x16x32_bf16 v[8:11], v[140:143], v[200:203], v[8:11]
	s_barrier
	s_add_u32 s98, s68, s58
	s_addc_u32 s99, s69, 0
	s_add_i32 s28, s28, s47
	s_mov_b32 m0, s28
	s_nop 0
	global_load_lds_dwordx4 v176, s[98:99]
	s_add_i32 m0, s28, 0x2000
	s_nop 0
	global_load_lds_dwordx4 v156, s[98:99]
	s_waitcnt vmcnt(6)
	s_barrier
	v_mfma_f32_16x16x32_bf16 v[52:55], v[204:207], v[144:147], v[52:55]
	v_mfma_f32_16x16x32_bf16 v[48:51], v[212:215], v[144:147], v[48:51]
	v_mfma_f32_16x16x32_bf16 v[36:39], v[204:207], v[162:165], v[36:39]
	v_mfma_f32_16x16x32_bf16 v[32:35], v[212:215], v[162:165], v[32:35]
	v_mfma_f32_16x16x32_bf16 v[20:23], v[204:207], v[170:173], v[20:23]
	v_mfma_f32_16x16x32_bf16 v[16:19], v[212:215], v[170:173], v[16:19]
	v_mfma_f32_16x16x32_bf16 v[4:7], v[204:207], v[196:199], v[4:7]
	v_mfma_f32_16x16x32_bf16 v[0:3], v[212:215], v[196:199], v[0:3]
	v_mfma_f32_16x16x32_bf16 v[52:55], v[208:211], v[148:151], v[52:55]
	v_mfma_f32_16x16x32_bf16 v[48:51], v[232:235], v[148:151], v[48:51]
	v_mfma_f32_16x16x32_bf16 v[36:39], v[208:211], v[166:169], v[36:39]
	v_mfma_f32_16x16x32_bf16 v[32:35], v[232:235], v[166:169], v[32:35]
	v_mfma_f32_16x16x32_bf16 v[20:23], v[208:211], v[188:191], v[20:23]
	v_mfma_f32_16x16x32_bf16 v[16:19], v[232:235], v[188:191], v[16:19]
	v_mfma_f32_16x16x32_bf16 v[4:7], v[208:211], v[200:203], v[4:7]
	v_mfma_f32_16x16x32_bf16 v[0:3], v[232:235], v[200:203], v[0:3]
	s_add_i32 s28, 0, 0x18000
	s_barrier
	ds_read_b128 v[128:131], v174 offset:32768
	ds_read_b128 v[132:135], v174 offset:33792
	ds_read_b128 v[136:139], v174 offset:34816
	ds_read_b128 v[140:143], v174 offset:35840
	ds_read_b128 v[144:147], v195 offset:32768
	ds_read_b128 v[162:165], v195 offset:34816
	ds_read_b128 v[170:173], v195 offset:36864
	ds_read_b128 v[196:199], v195 offset:38912
	ds_read_b128 v[148:151], v195 offset:33792
	ds_read_b128 v[166:169], v195 offset:35840
	ds_read_b128 v[188:191], v195 offset:37888
	ds_read_b128 v[200:203], v195 offset:39936
	s_add_u32 s100, s66, s58
	s_addc_u32 s101, s67, 0
	s_mov_b32 m0, s72
	s_nop 0
	global_load_lds_dwordx4 v152, s[100:101]
	s_mov_b32 m0, s73
	s_nop 0
	global_load_lds_dwordx4 v154, s[100:101]
	s_waitcnt lgkmcnt(8)
	s_barrier
	s_waitcnt lgkmcnt(7)
	v_mfma_f32_16x16x32_bf16 v[124:127], v[128:131], v[144:147], v[124:127]
	v_mfma_f32_16x16x32_bf16 v[120:123], v[136:139], v[144:147], v[120:123]
	s_waitcnt lgkmcnt(6)
	v_mfma_f32_16x16x32_bf16 v[108:111], v[128:131], v[162:165], v[108:111]
	v_mfma_f32_16x16x32_bf16 v[104:107], v[136:139], v[162:165], v[104:107]
	s_waitcnt lgkmcnt(5)
	v_mfma_f32_16x16x32_bf16 v[92:95], v[128:131], v[170:173], v[92:95]
	v_mfma_f32_16x16x32_bf16 v[88:91], v[136:139], v[170:173], v[88:91]
	s_waitcnt lgkmcnt(4)
	v_mfma_f32_16x16x32_bf16 v[76:79], v[128:131], v[196:199], v[76:79]
	v_mfma_f32_16x16x32_bf16 v[72:75], v[136:139], v[196:199], v[72:75]
	s_waitcnt lgkmcnt(3)
	v_mfma_f32_16x16x32_bf16 v[124:127], v[132:135], v[148:151], v[124:127]
	v_mfma_f32_16x16x32_bf16 v[120:123], v[140:143], v[148:151], v[120:123]
	s_waitcnt lgkmcnt(2)
	v_mfma_f32_16x16x32_bf16 v[108:111], v[132:135], v[166:169], v[108:111]
	v_mfma_f32_16x16x32_bf16 v[104:107], v[140:143], v[166:169], v[104:107]
	s_waitcnt lgkmcnt(1)
	v_mfma_f32_16x16x32_bf16 v[92:95], v[132:135], v[188:191], v[92:95]
	v_mfma_f32_16x16x32_bf16 v[88:91], v[140:143], v[188:191], v[88:91]
	s_waitcnt lgkmcnt(0)
	v_mfma_f32_16x16x32_bf16 v[76:79], v[132:135], v[200:203], v[76:79]
	v_mfma_f32_16x16x32_bf16 v[72:75], v[140:143], v[200:203], v[72:75]
	s_barrier
	ds_read_b128 v[204:207], v174 offset:49152
	ds_read_b128 v[208:211], v174 offset:50176
	ds_read_b128 v[212:215], v174 offset:51200
	ds_read_b128 v[232:235], v174 offset:52224
	s_add_i32 s29, 0, 0x1c000
	s_add_i32 s28, s28, s47
	s_add_i32 m0, s28, 0xffffff80
	s_nop 0
	global_load_lds_dwordx4 v176, s[68:69] offset:128
	s_add_i32 m0, s28, 0x1f80
	s_nop 0
	global_load_lds_dwordx4 v156, s[68:69] offset:128
	s_barrier
	s_waitcnt lgkmcnt(3)
	v_mfma_f32_16x16x32_bf16 v[116:119], v[204:207], v[144:147], v[116:119]
	s_waitcnt lgkmcnt(1)
	v_mfma_f32_16x16x32_bf16 v[112:115], v[212:215], v[144:147], v[112:115]
	v_mfma_f32_16x16x32_bf16 v[100:103], v[204:207], v[162:165], v[100:103]
	v_mfma_f32_16x16x32_bf16 v[96:99], v[212:215], v[162:165], v[96:99]
	v_mfma_f32_16x16x32_bf16 v[84:87], v[204:207], v[170:173], v[84:87]
	v_mfma_f32_16x16x32_bf16 v[80:83], v[212:215], v[170:173], v[80:83]
	v_mfma_f32_16x16x32_bf16 v[68:71], v[204:207], v[196:199], v[68:71]
	v_mfma_f32_16x16x32_bf16 v[64:67], v[212:215], v[196:199], v[64:67]
	v_mfma_f32_16x16x32_bf16 v[116:119], v[208:211], v[148:151], v[116:119]
	s_waitcnt lgkmcnt(0)
	v_mfma_f32_16x16x32_bf16 v[112:115], v[232:235], v[148:151], v[112:115]
	v_mfma_f32_16x16x32_bf16 v[100:103], v[208:211], v[166:169], v[100:103]
	v_mfma_f32_16x16x32_bf16 v[96:99], v[232:235], v[166:169], v[96:99]
	v_mfma_f32_16x16x32_bf16 v[84:87], v[208:211], v[188:191], v[84:87]
	v_mfma_f32_16x16x32_bf16 v[80:83], v[232:235], v[188:191], v[80:83]
	v_mfma_f32_16x16x32_bf16 v[68:71], v[208:211], v[200:203], v[68:71]
	v_mfma_f32_16x16x32_bf16 v[64:67], v[232:235], v[200:203], v[64:67]
	s_add_i32 m0, s74, 0xffffff80
	s_barrier
	ds_read_b128 v[144:147], v195 offset:49152
	ds_read_b128 v[162:165], v195 offset:51200
	ds_read_b128 v[170:173], v195 offset:53248
	ds_read_b128 v[196:199], v195 offset:55296
	ds_read_b128 v[148:151], v195 offset:50176
	ds_read_b128 v[166:169], v195 offset:52224
	ds_read_b128 v[188:191], v195 offset:54272
	ds_read_b128 v[200:203], v195 offset:56320
	global_load_lds_dwordx4 v152, s[66:67] offset:128
	s_add_i32 m0, s75, 0xffffff80
	s_nop 0
	global_load_lds_dwordx4 v154, s[66:67] offset:128
	s_barrier
	s_waitcnt lgkmcnt(7)
	v_mfma_f32_16x16x32_bf16 v[60:63], v[128:131], v[144:147], v[60:63]
	v_mfma_f32_16x16x32_bf16 v[56:59], v[136:139], v[144:147], v[56:59]
	s_waitcnt lgkmcnt(6)
	v_mfma_f32_16x16x32_bf16 v[44:47], v[128:131], v[162:165], v[44:47]
	v_mfma_f32_16x16x32_bf16 v[40:43], v[136:139], v[162:165], v[40:43]
	s_waitcnt lgkmcnt(5)
	v_mfma_f32_16x16x32_bf16 v[28:31], v[128:131], v[170:173], v[28:31]
	v_mfma_f32_16x16x32_bf16 v[24:27], v[136:139], v[170:173], v[24:27]
	s_waitcnt lgkmcnt(4)
	v_mfma_f32_16x16x32_bf16 v[12:15], v[128:131], v[196:199], v[12:15]
	v_mfma_f32_16x16x32_bf16 v[8:11], v[136:139], v[196:199], v[8:11]
	s_waitcnt lgkmcnt(3)
	v_mfma_f32_16x16x32_bf16 v[60:63], v[132:135], v[148:151], v[60:63]
	v_mfma_f32_16x16x32_bf16 v[56:59], v[140:143], v[148:151], v[56:59]
	s_waitcnt lgkmcnt(2)
	v_mfma_f32_16x16x32_bf16 v[44:47], v[132:135], v[166:169], v[44:47]
	v_mfma_f32_16x16x32_bf16 v[40:43], v[140:143], v[166:169], v[40:43]
	s_waitcnt lgkmcnt(1)
	v_mfma_f32_16x16x32_bf16 v[28:31], v[132:135], v[188:191], v[28:31]
	v_mfma_f32_16x16x32_bf16 v[24:27], v[140:143], v[188:191], v[24:27]
	s_waitcnt lgkmcnt(0)
	v_mfma_f32_16x16x32_bf16 v[12:15], v[132:135], v[200:203], v[12:15]
	v_mfma_f32_16x16x32_bf16 v[8:11], v[140:143], v[200:203], v[8:11]
	s_barrier
	s_add_i32 s28, s29, s47
	s_add_i32 m0, s28, 0xffffff80
	s_nop 0
	global_load_lds_dwordx4 v176, s[98:99] offset:128
	s_add_i32 m0, s28, 0x1f80
	s_nop 0
	global_load_lds_dwordx4 v156, s[98:99] offset:128
	s_waitcnt vmcnt(6)
	s_barrier
	v_mfma_f32_16x16x32_bf16 v[52:55], v[204:207], v[144:147], v[52:55]
	v_mfma_f32_16x16x32_bf16 v[48:51], v[212:215], v[144:147], v[48:51]
	v_mfma_f32_16x16x32_bf16 v[36:39], v[204:207], v[162:165], v[36:39]
	v_mfma_f32_16x16x32_bf16 v[32:35], v[212:215], v[162:165], v[32:35]
	v_mfma_f32_16x16x32_bf16 v[20:23], v[204:207], v[170:173], v[20:23]
	v_mfma_f32_16x16x32_bf16 v[16:19], v[212:215], v[170:173], v[16:19]
	v_mfma_f32_16x16x32_bf16 v[4:7], v[204:207], v[196:199], v[4:7]
	v_mfma_f32_16x16x32_bf16 v[0:3], v[212:215], v[196:199], v[0:3]
	v_mfma_f32_16x16x32_bf16 v[52:55], v[208:211], v[148:151], v[52:55]
	v_mfma_f32_16x16x32_bf16 v[48:51], v[232:235], v[148:151], v[48:51]
	v_mfma_f32_16x16x32_bf16 v[36:39], v[208:211], v[166:169], v[36:39]
	v_mfma_f32_16x16x32_bf16 v[32:35], v[232:235], v[166:169], v[32:35]
	v_mfma_f32_16x16x32_bf16 v[20:23], v[208:211], v[188:191], v[20:23]
	v_mfma_f32_16x16x32_bf16 v[16:19], v[232:235], v[188:191], v[16:19]
	v_mfma_f32_16x16x32_bf16 v[4:7], v[208:211], v[200:203], v[4:7]
	v_mfma_f32_16x16x32_bf16 v[0:3], v[232:235], v[200:203], v[0:3]
	s_add_u32 s64, s64, 0x100
	s_addc_u32 s65, s65, 0
	s_add_u32 s91, s91, 0x100
	s_addc_u32 vcc_lo, vcc_lo, 0
	s_cmp_lt_i32 vcc_hi, s76
	s_mov_b32 s66, vcc_hi
	s_barrier
	s_cbranch_scc1 .LBB0_1114
	s_lshl_b32 s28, s84, 8
	v_mov_b32_e32 v128, v193
	v_mov_b32_e32 v129, v192
	s_add_i32 s28, s28, s78
	s_lshl_b32 s64, s24, 2
	v_add_u32_e32 v166, s28, v129
	s_lshl_b32 s28, s24, 8
	s_or_b32 s28, s28, s79
	v_lshl_add_u32 v162, v128, 3, s28
	v_ashrrev_i32_e32 v163, 31, v162
	v_lshlrev_b64 v[204:205], 1, v[162:163]
	v_ashrrev_i32_e32 v167, 31, v166
	v_lshl_add_u64 v[164:165], s[12:13], 0, v[204:205]
	v_lshlrev_b64 v[206:207], 11, v[166:167]
	v_cmp_eq_u32_e32 vcc, 0, v128
	v_lshl_add_u64 v[128:129], v[164:165], 0, v[206:207]
	global_load_dwordx4 v[196:199], v[128:129], off
	global_load_dwordx4 v[200:203], v[128:129], off offset:256
	v_add_u32_e32 v188, 16, v166
	v_ashrrev_i32_e32 v189, 31, v188
	v_add_u32_e32 v172, 32, v166
	v_lshlrev_b64 v[190:191], 11, v[188:189]
	v_ashrrev_i32_e32 v173, 31, v172
	v_add_u32_e32 v168, 48, v166
	v_lshl_add_u64 v[128:129], v[164:165], 0, v[190:191]
	v_lshlrev_b64 v[174:175], 11, v[172:173]
	v_ashrrev_i32_e32 v169, 31, v168
	global_load_dwordx4 v[148:151], v[128:129], off
	global_load_dwordx4 v[144:147], v[128:129], off offset:256
	v_lshl_add_u64 v[128:129], v[164:165], 0, v[174:175]
	v_lshlrev_b64 v[170:171], 11, v[168:169]
	global_load_dwordx4 v[140:143], v[128:129], off
	global_load_dwordx4 v[136:139], v[128:129], off offset:256
	v_lshl_add_u64 v[128:129], v[164:165], 0, v[170:171]
	global_load_dwordx4 v[132:135], v[128:129], off
	s_nop 0
	global_load_dwordx4 v[128:131], v[128:129], off offset:256
	v_lshl_add_u64 v[206:207], s[12:13], 0, v[206:207]
	v_lshl_add_u64 v[204:205], v[206:207], 0, v[204:205]
	s_ashr_i32 s65, s64, 31
	s_waitcnt vmcnt(0)
	v_lshlrev_b32_e32 v208, 16, v196
	v_and_b32_e32 v209, 0xffff0000, v196
	v_lshlrev_b32_e32 v196, 16, v197
	v_and_b32_e32 v197, 0xffff0000, v197
	v_lshlrev_b32_e32 v210, 16, v198
	v_and_b32_e32 v211, 0xffff0000, v198
	v_lshlrev_b32_e32 v198, 16, v199
	v_and_b32_e32 v199, 0xffff0000, v199
	v_pk_fma_f32 v[126:127], s[62:63], v[126:127], v[196:197]
	v_pk_fma_f32 v[124:125], s[10:11], v[124:125], v[208:209]
	v_pk_fma_f32 v[196:197], s[62:63], v[122:123], v[198:199]
	v_pk_fma_f32 v[198:199], s[10:11], v[120:121], v[210:211]
	v_cvt_pk_bf16_f32 v120, v124, v125
	v_cvt_pk_bf16_f32 v121, v126, v127
	s_nop 0
	v_cvt_pk_bf16_f32 v122, v198, v199
	v_cvt_pk_bf16_f32 v123, v196, v197
	global_store_dwordx4 v[204:205], v[120:123], off
	s_nop 1
	v_pk_mul_f32 v[120:121], v[198:199], v[198:199]
	v_pk_mul_f32 v[122:123], v[196:197], v[196:197]
	v_pk_fma_f32 v[120:121], v[124:125], v[124:125], v[120:121]
	v_pk_fma_f32 v[122:123], v[126:127], v[126:127], v[122:123]
	v_add_f32_e32 v120, v120, v121
	v_add_f32_e32 v121, v122, v123
	v_add_f32_e32 v196, v120, v121
	v_lshlrev_b32_e32 v120, 16, v200
	v_and_b32_e32 v121, 0xffff0000, v200
	v_lshlrev_b32_e32 v122, 16, v201
	v_and_b32_e32 v123, 0xffff0000, v201
	v_lshlrev_b32_e32 v124, 16, v202
	v_and_b32_e32 v125, 0xffff0000, v202
	v_lshlrev_b32_e32 v126, 16, v203
	v_and_b32_e32 v127, 0xffff0000, v203
	v_pk_fma_f32 v[118:119], s[62:63], v[118:119], v[122:123]
	v_pk_fma_f32 v[116:117], s[10:11], v[116:117], v[120:121]
	v_pk_fma_f32 v[120:121], s[62:63], v[114:115], v[126:127]
	v_pk_fma_f32 v[122:123], s[10:11], v[112:113], v[124:125]
	v_cvt_pk_bf16_f32 v112, v116, v117
	v_cvt_pk_bf16_f32 v113, v118, v119
	s_nop 0
	v_cvt_pk_bf16_f32 v114, v122, v123
	v_cvt_pk_bf16_f32 v115, v120, v121
	global_store_dwordx4 v[204:205], v[112:115], off offset:256
	s_nop 1
	v_pk_mul_f32 v[112:113], v[122:123], v[122:123]
	v_pk_mul_f32 v[114:115], v[120:121], v[120:121]
	v_pk_fma_f32 v[112:113], v[116:117], v[116:117], v[112:113]
	v_pk_fma_f32 v[114:115], v[118:119], v[118:119], v[114:115]
	v_add_f32_e32 v112, v112, v113
	v_add_f32_e32 v113, v114, v115
	v_add_f32_e32 v112, v112, v113
	v_add_f32_e32 v112, v196, v112
	v_mov_b32_e32 v113, v112
	s_waitcnt lgkmcnt(0)
	s_nop 0
	v_permlane16_swap_b32 v112, v113
	v_add_f32_e32 v112, v112, v113
	v_mov_b32_e32 v113, v112
	s_nop 1
	v_permlane32_swap_b32 v112, v113
	s_and_saveexec_b64 s[66:67], vcc
	s_cbranch_execz .LBB0_1117
	v_lshlrev_b64 v[114:115], 6, v[166:167]
	v_lshl_add_u64 v[114:115], s[8:9], 0, v[114:115]
	v_lshl_add_u64 v[114:115], s[64:65], 2, v[114:115]
	s_lshl_b32 s24, s77, 2
	v_lshl_add_u64 v[114:115], v[114:115], 0, s[24:25]
	s_waitcnt lgkmcnt(0)
	v_add_f32_e32 v112, v112, v113
	global_store_dword v[114:115], v112, off

.LBB0_1282:
	ds_read_b128 v[128:131], v174
	ds_read_b128 v[132:135], v174 offset:1024
	ds_read_b128 v[136:139], v174 offset:2048
	ds_read_b128 v[140:143], v174 offset:3072
	ds_read_b128 v[144:147], v196
	ds_read_b128 v[162:165], v196 offset:2048
	ds_read_b128 v[170:173], v196 offset:4096
	ds_read_b128 v[198:201], v196 offset:6144
	ds_read_b128 v[148:151], v196 offset:1024
	ds_read_b128 v[166:169], v196 offset:3072
	ds_read_b128 v[188:191], v196 offset:5120
	ds_read_b128 v[202:205], v196 offset:7168
	s_add_i32 s81, s60, 2
	s_add_u32 s28, s58, 0x80
	s_addc_u32 s29, s59, 0
	s_add_i32 s82, 0, 0x10000
	s_cmp_eq_u32 s5, s60
	s_cselect_b32 s60, s56, s28
	s_cselect_b32 s61, s57, s29
	s_cselect_b32 s63, s3, s80
	s_cselect_b32 s62, s2, s21
	s_add_i32 m0, s66, 0xc000
	s_nop 0
	global_load_lds_dwordx4 v158, s[58:59]
	s_add_i32 m0, s66, 0xe000
	s_nop 0
	global_load_lds_dwordx4 v160, s[58:59]
	s_waitcnt lgkmcnt(8)
	s_barrier
	s_waitcnt lgkmcnt(7)
	v_mfma_f32_16x16x32_bf16 v[124:127], v[128:131], v[144:147], v[124:127]
	v_mfma_f32_16x16x32_bf16 v[120:123], v[136:139], v[144:147], v[120:123]
	s_waitcnt lgkmcnt(6)
	v_mfma_f32_16x16x32_bf16 v[108:111], v[128:131], v[162:165], v[108:111]
	v_mfma_f32_16x16x32_bf16 v[104:107], v[136:139], v[162:165], v[104:107]
	s_waitcnt lgkmcnt(5)
	v_mfma_f32_16x16x32_bf16 v[92:95], v[128:131], v[170:173], v[92:95]
	v_mfma_f32_16x16x32_bf16 v[88:91], v[136:139], v[170:173], v[88:91]
	s_waitcnt lgkmcnt(4)
	v_mfma_f32_16x16x32_bf16 v[76:79], v[128:131], v[198:201], v[76:79]
	v_mfma_f32_16x16x32_bf16 v[72:75], v[136:139], v[198:201], v[72:75]
	s_waitcnt lgkmcnt(3)
	v_mfma_f32_16x16x32_bf16 v[124:127], v[132:135], v[148:151], v[124:127]
	v_mfma_f32_16x16x32_bf16 v[120:123], v[140:143], v[148:151], v[120:123]
	s_waitcnt lgkmcnt(2)
	v_mfma_f32_16x16x32_bf16 v[108:111], v[132:135], v[166:169], v[108:111]
	v_mfma_f32_16x16x32_bf16 v[104:107], v[140:143], v[166:169], v[104:107]
	s_waitcnt lgkmcnt(1)
	v_mfma_f32_16x16x32_bf16 v[92:95], v[132:135], v[188:191], v[92:95]
	v_mfma_f32_16x16x32_bf16 v[88:91], v[140:143], v[188:191], v[88:91]
	s_waitcnt lgkmcnt(0)
	v_mfma_f32_16x16x32_bf16 v[76:79], v[132:135], v[202:205], v[76:79]
	v_mfma_f32_16x16x32_bf16 v[72:75], v[140:143], v[202:205], v[72:75]
	s_barrier
	ds_read_b128 v[206:209], v174 offset:16384
	ds_read_b128 v[210:213], v174 offset:17408
	ds_read_b128 v[214:217], v174 offset:18432
	ds_read_b128 v[232:235], v174 offset:19456
	s_add_i32 s28, 0, 0x14000
	s_add_i32 s29, s82, s65
	s_mov_b32 m0, s29
	s_nop 0
	global_load_lds_dwordx4 v176, s[62:63]
	s_add_i32 m0, s29, 0x2000
	s_nop 0
	global_load_lds_dwordx4 v156, s[62:63]
	s_barrier
	s_waitcnt lgkmcnt(3)
	v_mfma_f32_16x16x32_bf16 v[116:119], v[206:209], v[144:147], v[116:119]
	s_waitcnt lgkmcnt(1)
	v_mfma_f32_16x16x32_bf16 v[112:115], v[214:217], v[144:147], v[112:115]
	v_mfma_f32_16x16x32_bf16 v[100:103], v[206:209], v[162:165], v[100:103]
	v_mfma_f32_16x16x32_bf16 v[96:99], v[214:217], v[162:165], v[96:99]
	v_mfma_f32_16x16x32_bf16 v[84:87], v[206:209], v[170:173], v[84:87]
	v_mfma_f32_16x16x32_bf16 v[80:83], v[214:217], v[170:173], v[80:83]
	v_mfma_f32_16x16x32_bf16 v[68:71], v[206:209], v[198:201], v[68:71]
	v_mfma_f32_16x16x32_bf16 v[64:67], v[214:217], v[198:201], v[64:67]
	v_mfma_f32_16x16x32_bf16 v[116:119], v[210:213], v[148:151], v[116:119]
	s_waitcnt lgkmcnt(0)
	v_mfma_f32_16x16x32_bf16 v[112:115], v[232:235], v[148:151], v[112:115]
	v_mfma_f32_16x16x32_bf16 v[100:103], v[210:213], v[166:169], v[100:103]
	v_mfma_f32_16x16x32_bf16 v[96:99], v[232:235], v[166:169], v[96:99]
	v_mfma_f32_16x16x32_bf16 v[84:87], v[210:213], v[188:191], v[84:87]
	v_mfma_f32_16x16x32_bf16 v[80:83], v[232:235], v[188:191], v[80:83]
	v_mfma_f32_16x16x32_bf16 v[68:71], v[210:213], v[202:205], v[68:71]
	v_mfma_f32_16x16x32_bf16 v[64:67], v[232:235], v[202:205], v[64:67]
	s_mov_b32 m0, s66
	s_barrier
	ds_read_b128 v[144:147], v196 offset:16384
	ds_read_b128 v[162:165], v196 offset:18432
	ds_read_b128 v[170:173], v196 offset:20480
	ds_read_b128 v[198:201], v196 offset:22528
	ds_read_b128 v[148:151], v196 offset:17408
	ds_read_b128 v[166:169], v196 offset:19456
	ds_read_b128 v[188:191], v196 offset:21504
	ds_read_b128 v[202:205], v196 offset:23552
	global_load_lds_dwordx4 v152, s[60:61]
	s_mov_b32 m0, s67
	s_nop 0
	global_load_lds_dwordx4 v154, s[60:61]
	s_barrier
	s_waitcnt lgkmcnt(7)
	v_mfma_f32_16x16x32_bf16 v[60:63], v[128:131], v[144:147], v[60:63]
	v_mfma_f32_16x16x32_bf16 v[56:59], v[136:139], v[144:147], v[56:59]
	s_waitcnt lgkmcnt(6)
	v_mfma_f32_16x16x32_bf16 v[44:47], v[128:131], v[162:165], v[44:47]
	v_mfma_f32_16x16x32_bf16 v[40:43], v[136:139], v[162:165], v[40:43]
	s_waitcnt lgkmcnt(5)
	v_mfma_f32_16x16x32_bf16 v[28:31], v[128:131], v[170:173], v[28:31]
	v_mfma_f32_16x16x32_bf16 v[24:27], v[136:139], v[170:173], v[24:27]
	s_waitcnt lgkmcnt(4)
	v_mfma_f32_16x16x32_bf16 v[12:15], v[128:131], v[198:201], v[12:15]
	v_mfma_f32_16x16x32_bf16 v[8:11], v[136:139], v[198:201], v[8:11]
	s_waitcnt lgkmcnt(3)
	v_mfma_f32_16x16x32_bf16 v[60:63], v[132:135], v[148:151], v[60:63]
	v_mfma_f32_16x16x32_bf16 v[56:59], v[140:143], v[148:151], v[56:59]
	s_waitcnt lgkmcnt(2)
	v_mfma_f32_16x16x32_bf16 v[44:47], v[132:135], v[166:169], v[44:47]
	v_mfma_f32_16x16x32_bf16 v[40:43], v[140:143], v[166:169], v[40:43]
	s_waitcnt lgkmcnt(1)
	v_mfma_f32_16x16x32_bf16 v[28:31], v[132:135], v[188:191], v[28:31]
	v_mfma_f32_16x16x32_bf16 v[24:27], v[140:143], v[188:191], v[24:27]
	s_waitcnt lgkmcnt(0)
	v_mfma_f32_16x16x32_bf16 v[12:15], v[132:135], v[202:205], v[12:15]
	v_mfma_f32_16x16x32_bf16 v[8:11], v[140:143], v[202:205], v[8:11]
	s_barrier
	s_add_u32 s98, s62, s4
	s_addc_u32 s99, s63, 0
	s_add_i32 s28, s28, s65
	s_mov_b32 m0, s28
	s_nop 0
	global_load_lds_dwordx4 v176, s[98:99]
	s_add_i32 m0, s28, 0x2000
	s_nop 0
	global_load_lds_dwordx4 v156, s[98:99]
	s_waitcnt vmcnt(6)
	s_barrier
	v_mfma_f32_16x16x32_bf16 v[52:55], v[206:209], v[144:147], v[52:55]
	v_mfma_f32_16x16x32_bf16 v[48:51], v[214:217], v[144:147], v[48:51]
	v_mfma_f32_16x16x32_bf16 v[36:39], v[206:209], v[162:165], v[36:39]
	v_mfma_f32_16x16x32_bf16 v[32:35], v[214:217], v[162:165], v[32:35]
	v_mfma_f32_16x16x32_bf16 v[20:23], v[206:209], v[170:173], v[20:23]
	v_mfma_f32_16x16x32_bf16 v[16:19], v[214:217], v[170:173], v[16:19]
	v_mfma_f32_16x16x32_bf16 v[4:7], v[206:209], v[198:201], v[4:7]
	v_mfma_f32_16x16x32_bf16 v[0:3], v[214:217], v[198:201], v[0:3]
	v_mfma_f32_16x16x32_bf16 v[52:55], v[210:213], v[148:151], v[52:55]
	v_mfma_f32_16x16x32_bf16 v[48:51], v[232:235], v[148:151], v[48:51]
	v_mfma_f32_16x16x32_bf16 v[36:39], v[210:213], v[166:169], v[36:39]
	v_mfma_f32_16x16x32_bf16 v[32:35], v[232:235], v[166:169], v[32:35]
	v_mfma_f32_16x16x32_bf16 v[20:23], v[210:213], v[188:191], v[20:23]
	v_mfma_f32_16x16x32_bf16 v[16:19], v[232:235], v[188:191], v[16:19]
	v_mfma_f32_16x16x32_bf16 v[4:7], v[210:213], v[202:205], v[4:7]
	v_mfma_f32_16x16x32_bf16 v[0:3], v[232:235], v[202:205], v[0:3]
	s_add_i32 s28, 0, 0x18000
	s_barrier
	ds_read_b128 v[128:131], v174 offset:32768
	ds_read_b128 v[132:135], v174 offset:33792
	ds_read_b128 v[136:139], v174 offset:34816
	ds_read_b128 v[140:143], v174 offset:35840
	ds_read_b128 v[144:147], v196 offset:32768
	ds_read_b128 v[162:165], v196 offset:34816
	ds_read_b128 v[170:173], v196 offset:36864
	ds_read_b128 v[198:201], v196 offset:38912
	ds_read_b128 v[148:151], v196 offset:33792
	ds_read_b128 v[166:169], v196 offset:35840
	ds_read_b128 v[188:191], v196 offset:37888
	ds_read_b128 v[202:205], v196 offset:39936
	s_add_u32 s100, s60, s4
	s_addc_u32 s101, s61, 0
	s_mov_b32 m0, s68
	s_nop 0
	global_load_lds_dwordx4 v152, s[100:101]
	s_mov_b32 m0, s69
	s_nop 0
	global_load_lds_dwordx4 v154, s[100:101]
	s_waitcnt lgkmcnt(8)
	s_barrier
	s_waitcnt lgkmcnt(7)
	v_mfma_f32_16x16x32_bf16 v[124:127], v[128:131], v[144:147], v[124:127]
	v_mfma_f32_16x16x32_bf16 v[120:123], v[136:139], v[144:147], v[120:123]
	s_waitcnt lgkmcnt(6)
	v_mfma_f32_16x16x32_bf16 v[108:111], v[128:131], v[162:165], v[108:111]
	v_mfma_f32_16x16x32_bf16 v[104:107], v[136:139], v[162:165], v[104:107]
	s_waitcnt lgkmcnt(5)
	v_mfma_f32_16x16x32_bf16 v[92:95], v[128:131], v[170:173], v[92:95]
	v_mfma_f32_16x16x32_bf16 v[88:91], v[136:139], v[170:173], v[88:91]
	s_waitcnt lgkmcnt(4)
	v_mfma_f32_16x16x32_bf16 v[76:79], v[128:131], v[198:201], v[76:79]
	v_mfma_f32_16x16x32_bf16 v[72:75], v[136:139], v[198:201], v[72:75]
	s_waitcnt lgkmcnt(3)
	v_mfma_f32_16x16x32_bf16 v[124:127], v[132:135], v[148:151], v[124:127]
	v_mfma_f32_16x16x32_bf16 v[120:123], v[140:143], v[148:151], v[120:123]
	s_waitcnt lgkmcnt(2)
	v_mfma_f32_16x16x32_bf16 v[108:111], v[132:135], v[166:169], v[108:111]
	v_mfma_f32_16x16x32_bf16 v[104:107], v[140:143], v[166:169], v[104:107]
	s_waitcnt lgkmcnt(1)
	v_mfma_f32_16x16x32_bf16 v[92:95], v[132:135], v[188:191], v[92:95]
	v_mfma_f32_16x16x32_bf16 v[88:91], v[140:143], v[188:191], v[88:91]
	s_waitcnt lgkmcnt(0)
	v_mfma_f32_16x16x32_bf16 v[76:79], v[132:135], v[202:205], v[76:79]
	v_mfma_f32_16x16x32_bf16 v[72:75], v[140:143], v[202:205], v[72:75]
	s_barrier
	ds_read_b128 v[206:209], v174 offset:49152
	ds_read_b128 v[210:213], v174 offset:50176
	ds_read_b128 v[214:217], v174 offset:51200
	ds_read_b128 v[232:235], v174 offset:52224
	s_add_i32 s29, 0, 0x1c000
	s_add_i32 s28, s28, s65
	s_add_i32 m0, s28, 0xffffff80
	s_nop 0
	global_load_lds_dwordx4 v176, s[62:63] offset:128
	s_add_i32 m0, s28, 0x1f80
	s_nop 0
	global_load_lds_dwordx4 v156, s[62:63] offset:128
	s_barrier
	s_waitcnt lgkmcnt(3)
	v_mfma_f32_16x16x32_bf16 v[116:119], v[206:209], v[144:147], v[116:119]
	s_waitcnt lgkmcnt(1)
	v_mfma_f32_16x16x32_bf16 v[112:115], v[214:217], v[144:147], v[112:115]
	v_mfma_f32_16x16x32_bf16 v[100:103], v[206:209], v[162:165], v[100:103]
	v_mfma_f32_16x16x32_bf16 v[96:99], v[214:217], v[162:165], v[96:99]
	v_mfma_f32_16x16x32_bf16 v[84:87], v[206:209], v[170:173], v[84:87]
	v_mfma_f32_16x16x32_bf16 v[80:83], v[214:217], v[170:173], v[80:83]
	v_mfma_f32_16x16x32_bf16 v[68:71], v[206:209], v[198:201], v[68:71]
	v_mfma_f32_16x16x32_bf16 v[64:67], v[214:217], v[198:201], v[64:67]
	v_mfma_f32_16x16x32_bf16 v[116:119], v[210:213], v[148:151], v[116:119]
	s_waitcnt lgkmcnt(0)
	v_mfma_f32_16x16x32_bf16 v[112:115], v[232:235], v[148:151], v[112:115]
	v_mfma_f32_16x16x32_bf16 v[100:103], v[210:213], v[166:169], v[100:103]
	v_mfma_f32_16x16x32_bf16 v[96:99], v[232:235], v[166:169], v[96:99]
	v_mfma_f32_16x16x32_bf16 v[84:87], v[210:213], v[188:191], v[84:87]
	v_mfma_f32_16x16x32_bf16 v[80:83], v[232:235], v[188:191], v[80:83]
	v_mfma_f32_16x16x32_bf16 v[68:71], v[210:213], v[202:205], v[68:71]
	v_mfma_f32_16x16x32_bf16 v[64:67], v[232:235], v[202:205], v[64:67]
	s_add_i32 m0, s71, 0xffffff80
	s_barrier
	ds_read_b128 v[144:147], v196 offset:49152
	ds_read_b128 v[162:165], v196 offset:51200
	ds_read_b128 v[170:173], v196 offset:53248
	ds_read_b128 v[198:201], v196 offset:55296
	ds_read_b128 v[148:151], v196 offset:50176
	ds_read_b128 v[166:169], v196 offset:52224
	ds_read_b128 v[188:191], v196 offset:54272
	ds_read_b128 v[202:205], v196 offset:56320
	global_load_lds_dwordx4 v152, s[60:61] offset:128
	s_add_i32 m0, s72, 0xffffff80
	s_nop 0
	global_load_lds_dwordx4 v154, s[60:61] offset:128
	s_barrier
	s_waitcnt lgkmcnt(7)
	v_mfma_f32_16x16x32_bf16 v[60:63], v[128:131], v[144:147], v[60:63]
	v_mfma_f32_16x16x32_bf16 v[56:59], v[136:139], v[144:147], v[56:59]
	s_waitcnt lgkmcnt(6)
	v_mfma_f32_16x16x32_bf16 v[44:47], v[128:131], v[162:165], v[44:47]
	v_mfma_f32_16x16x32_bf16 v[40:43], v[136:139], v[162:165], v[40:43]
	s_waitcnt lgkmcnt(5)
	v_mfma_f32_16x16x32_bf16 v[28:31], v[128:131], v[170:173], v[28:31]
	v_mfma_f32_16x16x32_bf16 v[24:27], v[136:139], v[170:173], v[24:27]
	s_waitcnt lgkmcnt(4)
	v_mfma_f32_16x16x32_bf16 v[12:15], v[128:131], v[198:201], v[12:15]
	v_mfma_f32_16x16x32_bf16 v[8:11], v[136:139], v[198:201], v[8:11]
	s_waitcnt lgkmcnt(3)
	v_mfma_f32_16x16x32_bf16 v[60:63], v[132:135], v[148:151], v[60:63]
	v_mfma_f32_16x16x32_bf16 v[56:59], v[140:143], v[148:151], v[56:59]
	s_waitcnt lgkmcnt(2)
	v_mfma_f32_16x16x32_bf16 v[44:47], v[132:135], v[166:169], v[44:47]
	v_mfma_f32_16x16x32_bf16 v[40:43], v[140:143], v[166:169], v[40:43]
	s_waitcnt lgkmcnt(1)
	v_mfma_f32_16x16x32_bf16 v[28:31], v[132:135], v[188:191], v[28:31]
	v_mfma_f32_16x16x32_bf16 v[24:27], v[140:143], v[188:191], v[24:27]
	s_waitcnt lgkmcnt(0)
	v_mfma_f32_16x16x32_bf16 v[12:15], v[132:135], v[202:205], v[12:15]
	v_mfma_f32_16x16x32_bf16 v[8:11], v[140:143], v[202:205], v[8:11]
	s_barrier
	s_add_i32 s28, s29, s65
	s_add_i32 m0, s28, 0xffffff80
	s_nop 0
	global_load_lds_dwordx4 v176, s[98:99] offset:128
	s_add_i32 m0, s28, 0x1f80
	s_nop 0
	global_load_lds_dwordx4 v156, s[98:99] offset:128
	s_waitcnt vmcnt(6)
	s_barrier
	v_mfma_f32_16x16x32_bf16 v[52:55], v[206:209], v[144:147], v[52:55]
	v_mfma_f32_16x16x32_bf16 v[48:51], v[214:217], v[144:147], v[48:51]
	v_mfma_f32_16x16x32_bf16 v[36:39], v[206:209], v[162:165], v[36:39]
	v_mfma_f32_16x16x32_bf16 v[32:35], v[214:217], v[162:165], v[32:35]
	v_mfma_f32_16x16x32_bf16 v[20:23], v[206:209], v[170:173], v[20:23]
	v_mfma_f32_16x16x32_bf16 v[16:19], v[214:217], v[170:173], v[16:19]
	v_mfma_f32_16x16x32_bf16 v[4:7], v[206:209], v[198:201], v[4:7]
	v_mfma_f32_16x16x32_bf16 v[0:3], v[214:217], v[198:201], v[0:3]
	v_mfma_f32_16x16x32_bf16 v[52:55], v[210:213], v[148:151], v[52:55]
	v_mfma_f32_16x16x32_bf16 v[48:51], v[232:235], v[148:151], v[48:51]
	v_mfma_f32_16x16x32_bf16 v[36:39], v[210:213], v[166:169], v[36:39]
	v_mfma_f32_16x16x32_bf16 v[32:35], v[232:235], v[166:169], v[32:35]
	v_mfma_f32_16x16x32_bf16 v[20:23], v[210:213], v[188:191], v[20:23]
	v_mfma_f32_16x16x32_bf16 v[16:19], v[232:235], v[188:191], v[16:19]
	v_mfma_f32_16x16x32_bf16 v[4:7], v[210:213], v[202:205], v[4:7]
	v_mfma_f32_16x16x32_bf16 v[0:3], v[232:235], v[202:205], v[0:3]
	s_add_u32 s58, s58, 0x100
	s_addc_u32 s59, s59, 0
	s_add_u32 s21, s21, 0x100
	s_addc_u32 s80, s80, 0
	s_cmp_ge_i32 s81, s79
	s_mov_b32 s60, s81
	s_barrier
	s_cbranch_scc0 .LBB0_1282
	s_cmp_gt_i32 s24, -1
	s_mov_b64 s[58:59], -1
	s_cbranch_scc0 .LBB0_1285
	s_lshl_b64 s[58:59], s[24:25], 17
	v_mov_b32_e32 v128, v231
	s_add_u32 s58, s37, s58
	s_addc_u32 s59, s46, s59
	v_ashrrev_i32_e32 v129, 31, v128
	v_lshl_add_u64 v[128:129], v[128:129], 4, s[58:59]
	v_add_co_u32_e32 v134, vcc, s36, v128
	v_cvt_pk_bf16_f32 v130, v124, v125
	v_cvt_pk_bf16_f32 v131, v126, v127
	v_cvt_pk_bf16_f32 v132, v120, v121
	v_cvt_pk_bf16_f32 v133, v122, v123
	s_nop 1
	v_addc_co_u32_e32 v135, vcc, 0, v129, vcc
	s_movk_i32 s5, 0x4000
	global_store_dwordx4 v[128:129], v[130:133], off
	s_mov_b64 s[58:59], 0
	s_nop 0
	v_cvt_pk_bf16_f32 v130, v108, v109
	v_cvt_pk_bf16_f32 v131, v110, v111
	v_cvt_pk_bf16_f32 v132, v104, v105
	v_cvt_pk_bf16_f32 v133, v106, v107
	global_store_dwordx4 v[134:135], v[130:133], off
	v_add_co_u32_e32 v134, vcc, s5, v128
	s_movk_i32 s5, 0x6000
	s_nop 0
	v_addc_co_u32_e32 v135, vcc, 0, v129, vcc
	v_cvt_pk_bf16_f32 v130, v92, v93
	v_cvt_pk_bf16_f32 v131, v94, v95
	v_cvt_pk_bf16_f32 v132, v88, v89
	v_cvt_pk_bf16_f32 v133, v90, v91
	global_store_dwordx4 v[134:135], v[130:133], off
	v_add_co_u32_e32 v134, vcc, s5, v128
	s_nop 0
	v_cvt_pk_bf16_f32 v130, v76, v77
	v_cvt_pk_bf16_f32 v131, v78, v79
	v_cvt_pk_bf16_f32 v132, v72, v73
	v_cvt_pk_bf16_f32 v133, v74, v75
	s_nop 0
	v_addc_co_u32_e32 v135, vcc, 0, v129, vcc
	global_store_dwordx4 v[134:135], v[130:133], off
	v_add_co_u32_e32 v134, vcc, s92, v128
	s_mov_b32 s5, 0xa000
	s_nop 0
	v_addc_co_u32_e32 v135, vcc, 0, v129, vcc
	v_cvt_pk_bf16_f32 v130, v116, v117
	v_cvt_pk_bf16_f32 v131, v118, v119
	v_cvt_pk_bf16_f32 v132, v112, v113
	v_cvt_pk_bf16_f32 v133, v114, v115
	global_store_dwordx4 v[134:135], v[130:133], off
	v_add_co_u32_e32 v134, vcc, s5, v128
	s_mov_b32 s5, 0xc000
	s_nop 0
	v_addc_co_u32_e32 v135, vcc, 0, v129, vcc
	v_cvt_pk_bf16_f32 v130, v100, v101
	v_cvt_pk_bf16_f32 v131, v102, v103
	v_cvt_pk_bf16_f32 v132, v96, v97
	v_cvt_pk_bf16_f32 v133, v98, v99
	global_store_dwordx4 v[134:135], v[130:133], off
	v_add_co_u32_e32 v134, vcc, s5, v128
	s_mov_b32 s5, 0xe000
	s_nop 0
	v_addc_co_u32_e32 v135, vcc, 0, v129, vcc
	v_cvt_pk_bf16_f32 v130, v84, v85
	v_cvt_pk_bf16_f32 v131, v86, v87
	v_cvt_pk_bf16_f32 v132, v80, v81
	v_cvt_pk_bf16_f32 v133, v82, v83
	global_store_dwordx4 v[134:135], v[130:133], off
	v_add_co_u32_e32 v134, vcc, s5, v128
	s_mov_b32 s5, 0x10000
	s_nop 0
	v_addc_co_u32_e32 v135, vcc, 0, v129, vcc
	v_cvt_pk_bf16_f32 v130, v68, v69
	v_cvt_pk_bf16_f32 v131, v70, v71
	v_cvt_pk_bf16_f32 v132, v64, v65
	v_cvt_pk_bf16_f32 v133, v66, v67
	global_store_dwordx4 v[134:135], v[130:133], off
	v_add_co_u32_e32 v134, vcc, s5, v128
	s_mov_b32 s5, 0x12000
	s_nop 0
	v_addc_co_u32_e32 v135, vcc, 0, v129, vcc
	v_cvt_pk_bf16_f32 v130, v60, v61
	v_cvt_pk_bf16_f32 v131, v62, v63
	v_cvt_pk_bf16_f32 v132, v56, v57
	v_cvt_pk_bf16_f32 v133, v58, v59
	global_store_dwordx4 v[134:135], v[130:133], off
	v_add_co_u32_e32 v134, vcc, s5, v128
	s_mov_b32 s5, 0x14000
	s_nop 0
	v_addc_co_u32_e32 v135, vcc, 0, v129, vcc
	v_cvt_pk_bf16_f32 v130, v44, v45
	v_cvt_pk_bf16_f32 v131, v46, v47
	v_cvt_pk_bf16_f32 v132, v40, v41
	v_cvt_pk_bf16_f32 v133, v42, v43
	global_store_dwordx4 v[134:135], v[130:133], off
	v_add_co_u32_e32 v134, vcc, s5, v128
	s_mov_b32 s5, 0x16000
	s_nop 0
	v_addc_co_u32_e32 v135, vcc, 0, v129, vcc
	v_cvt_pk_bf16_f32 v130, v28, v29
	v_cvt_pk_bf16_f32 v131, v30, v31
	v_cvt_pk_bf16_f32 v132, v24, v25
	v_cvt_pk_bf16_f32 v133, v26, v27
	global_store_dwordx4 v[134:135], v[130:133], off
	v_add_co_u32_e32 v134, vcc, s5, v128
	s_mov_b32 s5, 0x18000
	s_nop 0
	v_addc_co_u32_e32 v135, vcc, 0, v129, vcc
	v_cvt_pk_bf16_f32 v130, v12, v13
	v_cvt_pk_bf16_f32 v131, v14, v15
	v_cvt_pk_bf16_f32 v132, v8, v9
	v_cvt_pk_bf16_f32 v133, v10, v11
	global_store_dwordx4 v[134:135], v[130:133], off
	v_add_co_u32_e32 v134, vcc, s5, v128
	s_mov_b32 s5, 0x1a000
	s_nop 0
	v_addc_co_u32_e32 v135, vcc, 0, v129, vcc
	v_cvt_pk_bf16_f32 v130, v52, v53
	v_cvt_pk_bf16_f32 v131, v54, v55
	v_cvt_pk_bf16_f32 v132, v48, v49
	v_cvt_pk_bf16_f32 v133, v50, v51
	global_store_dwordx4 v[134:135], v[130:133], off
	v_add_co_u32_e32 v134, vcc, s5, v128
	s_mov_b32 s5, 0x1c000
	s_nop 0
	v_addc_co_u32_e32 v135, vcc, 0, v129, vcc
	v_cvt_pk_bf16_f32 v130, v36, v37
	v_cvt_pk_bf16_f32 v131, v38, v39
	v_cvt_pk_bf16_f32 v132, v32, v33
	v_cvt_pk_bf16_f32 v133, v34, v35
	global_store_dwordx4 v[134:135], v[130:133], off
	v_add_co_u32_e32 v134, vcc, s5, v128
	s_nop 0
	v_cvt_pk_bf16_f32 v130, v20, v21
	v_cvt_pk_bf16_f32 v131, v22, v23
	v_cvt_pk_bf16_f32 v132, v16, v17
	v_cvt_pk_bf16_f32 v133, v18, v19
	s_nop 0
	v_addc_co_u32_e32 v135, vcc, 0, v129, vcc
	v_add_co_u32_e32 v128, vcc, 0x1e000, v128
	global_store_dwordx4 v[134:135], v[130:133], off
	s_nop 0
	v_addc_co_u32_e32 v129, vcc, 0, v129, vcc
	v_cvt_pk_bf16_f32 v130, v4, v5
	v_cvt_pk_bf16_f32 v131, v6, v7
	v_cvt_pk_bf16_f32 v132, v0, v1
	v_cvt_pk_bf16_f32 v133, v2, v3
	global_store_dwordx4 v[128:129], v[130:133], off

.LBB0_1436:
	ds_read_b128 v[128:131], v174
	ds_read_b128 v[132:135], v174 offset:1024
	ds_read_b128 v[136:139], v174 offset:2048
	ds_read_b128 v[140:143], v174 offset:3072
	ds_read_b128 v[144:147], v201
	ds_read_b128 v[152:155], v201 offset:2048
	ds_read_b128 v[170:173], v201 offset:4096
	ds_read_b128 v[192:195], v201 offset:6144
	ds_read_b128 v[148:151], v201 offset:1024
	ds_read_b128 v[166:169], v201 offset:3072
	ds_read_b128 v[188:191], v201 offset:5120
	ds_read_b128 v[202:205], v201 offset:7168
	s_add_u32 s28, s6, 0xfffc0080
	s_addc_u32 s29, s7, -1
	s_add_i32 s71, 0, 0x10000
	s_cmp_eq_u32 s70, 12
	s_cselect_b32 s53, s17, s29
	s_cselect_b32 s52, s66, s28
	s_cselect_b32 s51, s13, s69
	s_cselect_b32 s50, s67, s68
	s_add_i32 m0, s56, 0xc000
	s_nop 0
	global_load_lds_dwordx4 v162, s[6:7]
	s_add_i32 m0, s56, 0xe000
	s_nop 0
	global_load_lds_dwordx4 v164, s[6:7]
	s_waitcnt lgkmcnt(8)
	s_barrier
	s_waitcnt lgkmcnt(7)
	v_mfma_f32_16x16x32_bf16 v[124:127], v[128:131], v[144:147], v[124:127]
	v_mfma_f32_16x16x32_bf16 v[116:119], v[136:139], v[144:147], v[116:119]
	s_waitcnt lgkmcnt(6)
	v_mfma_f32_16x16x32_bf16 v[108:111], v[128:131], v[152:155], v[108:111]
	v_mfma_f32_16x16x32_bf16 v[100:103], v[136:139], v[152:155], v[100:103]
	s_waitcnt lgkmcnt(5)
	v_mfma_f32_16x16x32_bf16 v[92:95], v[128:131], v[170:173], v[92:95]
	v_mfma_f32_16x16x32_bf16 v[84:87], v[136:139], v[170:173], v[84:87]
	s_waitcnt lgkmcnt(4)
	v_mfma_f32_16x16x32_bf16 v[76:79], v[128:131], v[192:195], v[76:79]
	v_mfma_f32_16x16x32_bf16 v[68:71], v[136:139], v[192:195], v[68:71]
	s_waitcnt lgkmcnt(3)
	v_mfma_f32_16x16x32_bf16 v[124:127], v[132:135], v[148:151], v[124:127]
	v_mfma_f32_16x16x32_bf16 v[116:119], v[140:143], v[148:151], v[116:119]
	s_waitcnt lgkmcnt(2)
	v_mfma_f32_16x16x32_bf16 v[108:111], v[132:135], v[166:169], v[108:111]
	v_mfma_f32_16x16x32_bf16 v[100:103], v[140:143], v[166:169], v[100:103]
	s_waitcnt lgkmcnt(1)
	v_mfma_f32_16x16x32_bf16 v[92:95], v[132:135], v[188:191], v[92:95]
	v_mfma_f32_16x16x32_bf16 v[84:87], v[140:143], v[188:191], v[84:87]
	s_waitcnt lgkmcnt(0)
	v_mfma_f32_16x16x32_bf16 v[76:79], v[132:135], v[202:205], v[76:79]
	v_mfma_f32_16x16x32_bf16 v[68:71], v[140:143], v[202:205], v[68:71]
	s_barrier
	ds_read_b128 v[206:209], v174 offset:16384
	ds_read_b128 v[210:213], v174 offset:17408
	ds_read_b128 v[214:217], v174 offset:18432
	ds_read_b128 v[232:235], v174 offset:19456
	s_add_i32 s28, 0, 0x14000
	s_add_i32 s29, s71, s55
	s_mov_b32 m0, s29
	s_nop 0
	global_load_lds_dwordx4 v176, s[50:51]
	s_add_i32 m0, s29, 0x2000
	s_nop 0
	global_load_lds_dwordx4 v160, s[50:51]
	s_barrier
	s_waitcnt lgkmcnt(3)
	v_mfma_f32_16x16x32_bf16 v[120:123], v[206:209], v[144:147], v[120:123]
	s_waitcnt lgkmcnt(1)
	v_mfma_f32_16x16x32_bf16 v[112:115], v[214:217], v[144:147], v[112:115]
	v_mfma_f32_16x16x32_bf16 v[104:107], v[206:209], v[152:155], v[104:107]
	v_mfma_f32_16x16x32_bf16 v[96:99], v[214:217], v[152:155], v[96:99]
	v_mfma_f32_16x16x32_bf16 v[88:91], v[206:209], v[170:173], v[88:91]
	v_mfma_f32_16x16x32_bf16 v[80:83], v[214:217], v[170:173], v[80:83]
	v_mfma_f32_16x16x32_bf16 v[72:75], v[206:209], v[192:195], v[72:75]
	v_mfma_f32_16x16x32_bf16 v[64:67], v[214:217], v[192:195], v[64:67]
	v_mfma_f32_16x16x32_bf16 v[120:123], v[210:213], v[148:151], v[120:123]
	s_waitcnt lgkmcnt(0)
	v_mfma_f32_16x16x32_bf16 v[112:115], v[232:235], v[148:151], v[112:115]
	v_mfma_f32_16x16x32_bf16 v[104:107], v[210:213], v[166:169], v[104:107]
	v_mfma_f32_16x16x32_bf16 v[96:99], v[232:235], v[166:169], v[96:99]
	v_mfma_f32_16x16x32_bf16 v[88:91], v[210:213], v[188:191], v[88:91]
	v_mfma_f32_16x16x32_bf16 v[80:83], v[232:235], v[188:191], v[80:83]
	v_mfma_f32_16x16x32_bf16 v[72:75], v[210:213], v[202:205], v[72:75]
	v_mfma_f32_16x16x32_bf16 v[64:67], v[232:235], v[202:205], v[64:67]
	s_mov_b32 m0, s56
	s_barrier
	ds_read_b128 v[144:147], v201 offset:16384
	ds_read_b128 v[152:155], v201 offset:18432
	ds_read_b128 v[170:173], v201 offset:20480
	ds_read_b128 v[192:195], v201 offset:22528
	ds_read_b128 v[148:151], v201 offset:17408
	ds_read_b128 v[166:169], v201 offset:19456
	ds_read_b128 v[188:191], v201 offset:21504
	ds_read_b128 v[202:205], v201 offset:23552
	global_load_lds_dwordx4 v156, s[52:53]
	s_mov_b32 m0, s57
	s_nop 0
	global_load_lds_dwordx4 v158, s[52:53]
	s_barrier
	s_waitcnt lgkmcnt(7)
	v_mfma_f32_16x16x32_bf16 v[60:63], v[128:131], v[144:147], v[60:63]
	v_mfma_f32_16x16x32_bf16 v[52:55], v[136:139], v[144:147], v[52:55]
	s_waitcnt lgkmcnt(6)
	v_mfma_f32_16x16x32_bf16 v[44:47], v[128:131], v[152:155], v[44:47]
	v_mfma_f32_16x16x32_bf16 v[36:39], v[136:139], v[152:155], v[36:39]
	s_waitcnt lgkmcnt(5)
	v_mfma_f32_16x16x32_bf16 v[28:31], v[128:131], v[170:173], v[28:31]
	v_mfma_f32_16x16x32_bf16 v[20:23], v[136:139], v[170:173], v[20:23]
	s_waitcnt lgkmcnt(4)
	v_mfma_f32_16x16x32_bf16 v[12:15], v[128:131], v[192:195], v[12:15]
	v_mfma_f32_16x16x32_bf16 v[4:7], v[136:139], v[192:195], v[4:7]
	s_waitcnt lgkmcnt(3)
	v_mfma_f32_16x16x32_bf16 v[60:63], v[132:135], v[148:151], v[60:63]
	v_mfma_f32_16x16x32_bf16 v[52:55], v[140:143], v[148:151], v[52:55]
	s_waitcnt lgkmcnt(2)
	v_mfma_f32_16x16x32_bf16 v[44:47], v[132:135], v[166:169], v[44:47]
	v_mfma_f32_16x16x32_bf16 v[36:39], v[140:143], v[166:169], v[36:39]
	s_waitcnt lgkmcnt(1)
	v_mfma_f32_16x16x32_bf16 v[28:31], v[132:135], v[188:191], v[28:31]
	v_mfma_f32_16x16x32_bf16 v[20:23], v[140:143], v[188:191], v[20:23]
	s_waitcnt lgkmcnt(0)
	v_mfma_f32_16x16x32_bf16 v[12:15], v[132:135], v[202:205], v[12:15]
	v_mfma_f32_16x16x32_bf16 v[4:7], v[140:143], v[202:205], v[4:7]
	s_barrier
	s_add_u32 s72, s50, 0x40000
	s_addc_u32 s73, s51, 0
	s_add_i32 s28, s28, s55
	s_mov_b32 m0, s28
	s_nop 0
	global_load_lds_dwordx4 v176, s[72:73]
	s_add_i32 m0, s28, 0x2000
	s_nop 0
	global_load_lds_dwordx4 v160, s[72:73]
	s_waitcnt vmcnt(6)
	s_barrier
	v_mfma_f32_16x16x32_bf16 v[56:59], v[206:209], v[144:147], v[56:59]
	v_mfma_f32_16x16x32_bf16 v[48:51], v[214:217], v[144:147], v[48:51]
	v_mfma_f32_16x16x32_bf16 v[40:43], v[206:209], v[152:155], v[40:43]
	v_mfma_f32_16x16x32_bf16 v[32:35], v[214:217], v[152:155], v[32:35]
	v_mfma_f32_16x16x32_bf16 v[24:27], v[206:209], v[170:173], v[24:27]
	v_mfma_f32_16x16x32_bf16 v[16:19], v[214:217], v[170:173], v[16:19]
	v_mfma_f32_16x16x32_bf16 v[8:11], v[206:209], v[192:195], v[8:11]
	v_mfma_f32_16x16x32_bf16 v[0:3], v[214:217], v[192:195], v[0:3]
	v_mfma_f32_16x16x32_bf16 v[56:59], v[210:213], v[148:151], v[56:59]
	v_mfma_f32_16x16x32_bf16 v[48:51], v[232:235], v[148:151], v[48:51]
	v_mfma_f32_16x16x32_bf16 v[40:43], v[210:213], v[166:169], v[40:43]
	v_mfma_f32_16x16x32_bf16 v[32:35], v[232:235], v[166:169], v[32:35]
	v_mfma_f32_16x16x32_bf16 v[24:27], v[210:213], v[188:191], v[24:27]
	v_mfma_f32_16x16x32_bf16 v[16:19], v[232:235], v[188:191], v[16:19]
	v_mfma_f32_16x16x32_bf16 v[8:11], v[210:213], v[202:205], v[8:11]
	v_mfma_f32_16x16x32_bf16 v[0:3], v[232:235], v[202:205], v[0:3]
	s_add_i32 s28, 0, 0x18000
	s_barrier
	ds_read_b128 v[128:131], v174 offset:32768
	ds_read_b128 v[132:135], v174 offset:33792
	ds_read_b128 v[136:139], v174 offset:34816
	ds_read_b128 v[140:143], v174 offset:35840
	ds_read_b128 v[144:147], v201 offset:32768
	ds_read_b128 v[152:155], v201 offset:34816
	ds_read_b128 v[170:173], v201 offset:36864
	ds_read_b128 v[192:195], v201 offset:38912
	ds_read_b128 v[148:151], v201 offset:33792
	ds_read_b128 v[166:169], v201 offset:35840
	ds_read_b128 v[188:191], v201 offset:37888
	ds_read_b128 v[202:205], v201 offset:39936
	s_add_u32 s98, s52, 0x40000
	s_addc_u32 s99, s53, 0
	s_mov_b32 m0, s58
	s_nop 0
	global_load_lds_dwordx4 v156, s[98:99]
	s_mov_b32 m0, s59
	s_nop 0
	global_load_lds_dwordx4 v158, s[98:99]
	s_waitcnt lgkmcnt(8)
	s_barrier
	s_waitcnt lgkmcnt(7)
	v_mfma_f32_16x16x32_bf16 v[124:127], v[128:131], v[144:147], v[124:127]
	v_mfma_f32_16x16x32_bf16 v[116:119], v[136:139], v[144:147], v[116:119]
	s_waitcnt lgkmcnt(6)
	v_mfma_f32_16x16x32_bf16 v[108:111], v[128:131], v[152:155], v[108:111]
	v_mfma_f32_16x16x32_bf16 v[100:103], v[136:139], v[152:155], v[100:103]
	s_waitcnt lgkmcnt(5)
	v_mfma_f32_16x16x32_bf16 v[92:95], v[128:131], v[170:173], v[92:95]
	v_mfma_f32_16x16x32_bf16 v[84:87], v[136:139], v[170:173], v[84:87]
	s_waitcnt lgkmcnt(4)
	v_mfma_f32_16x16x32_bf16 v[76:79], v[128:131], v[192:195], v[76:79]
	v_mfma_f32_16x16x32_bf16 v[68:71], v[136:139], v[192:195], v[68:71]
	s_waitcnt lgkmcnt(3)
	v_mfma_f32_16x16x32_bf16 v[124:127], v[132:135], v[148:151], v[124:127]
	v_mfma_f32_16x16x32_bf16 v[116:119], v[140:143], v[148:151], v[116:119]
	s_waitcnt lgkmcnt(2)
	v_mfma_f32_16x16x32_bf16 v[108:111], v[132:135], v[166:169], v[108:111]
	v_mfma_f32_16x16x32_bf16 v[100:103], v[140:143], v[166:169], v[100:103]
	s_waitcnt lgkmcnt(1)
	v_mfma_f32_16x16x32_bf16 v[92:95], v[132:135], v[188:191], v[92:95]
	v_mfma_f32_16x16x32_bf16 v[84:87], v[140:143], v[188:191], v[84:87]
	s_waitcnt lgkmcnt(0)
	v_mfma_f32_16x16x32_bf16 v[76:79], v[132:135], v[202:205], v[76:79]
	v_mfma_f32_16x16x32_bf16 v[68:71], v[140:143], v[202:205], v[68:71]
	s_barrier
	ds_read_b128 v[206:209], v174 offset:49152
	ds_read_b128 v[210:213], v174 offset:50176
	ds_read_b128 v[214:217], v174 offset:51200
	ds_read_b128 v[232:235], v174 offset:52224
	s_add_i32 s29, 0, 0x1c000
	s_add_i32 s28, s28, s55
	s_add_i32 m0, s28, 0xffffff80
	s_nop 0
	global_load_lds_dwordx4 v176, s[50:51] offset:128
	s_add_i32 m0, s28, 0x1f80
	s_nop 0
	global_load_lds_dwordx4 v160, s[50:51] offset:128
	s_barrier
	s_waitcnt lgkmcnt(3)
	v_mfma_f32_16x16x32_bf16 v[120:123], v[206:209], v[144:147], v[120:123]
	s_waitcnt lgkmcnt(1)
	v_mfma_f32_16x16x32_bf16 v[112:115], v[214:217], v[144:147], v[112:115]
	v_mfma_f32_16x16x32_bf16 v[104:107], v[206:209], v[152:155], v[104:107]
	v_mfma_f32_16x16x32_bf16 v[96:99], v[214:217], v[152:155], v[96:99]
	v_mfma_f32_16x16x32_bf16 v[88:91], v[206:209], v[170:173], v[88:91]
	v_mfma_f32_16x16x32_bf16 v[80:83], v[214:217], v[170:173], v[80:83]
	v_mfma_f32_16x16x32_bf16 v[72:75], v[206:209], v[192:195], v[72:75]
	v_mfma_f32_16x16x32_bf16 v[64:67], v[214:217], v[192:195], v[64:67]
	v_mfma_f32_16x16x32_bf16 v[120:123], v[210:213], v[148:151], v[120:123]
	s_waitcnt lgkmcnt(0)
	v_mfma_f32_16x16x32_bf16 v[112:115], v[232:235], v[148:151], v[112:115]
	v_mfma_f32_16x16x32_bf16 v[104:107], v[210:213], v[166:169], v[104:107]
	v_mfma_f32_16x16x32_bf16 v[96:99], v[232:235], v[166:169], v[96:99]
	v_mfma_f32_16x16x32_bf16 v[88:91], v[210:213], v[188:191], v[88:91]
	v_mfma_f32_16x16x32_bf16 v[80:83], v[232:235], v[188:191], v[80:83]
	v_mfma_f32_16x16x32_bf16 v[72:75], v[210:213], v[202:205], v[72:75]
	v_mfma_f32_16x16x32_bf16 v[64:67], v[232:235], v[202:205], v[64:67]
	s_add_i32 m0, s62, 0xffffff80
	s_barrier
	ds_read_b128 v[144:147], v201 offset:49152
	ds_read_b128 v[152:155], v201 offset:51200
	ds_read_b128 v[170:173], v201 offset:53248
	ds_read_b128 v[192:195], v201 offset:55296
	ds_read_b128 v[148:151], v201 offset:50176
	ds_read_b128 v[166:169], v201 offset:52224
	ds_read_b128 v[188:191], v201 offset:54272
	ds_read_b128 v[202:205], v201 offset:56320
	global_load_lds_dwordx4 v156, s[52:53] offset:128
	s_add_i32 m0, s63, 0xffffff80
	s_nop 0
	global_load_lds_dwordx4 v158, s[52:53] offset:128
	s_barrier
	s_waitcnt lgkmcnt(7)
	v_mfma_f32_16x16x32_bf16 v[60:63], v[128:131], v[144:147], v[60:63]
	v_mfma_f32_16x16x32_bf16 v[52:55], v[136:139], v[144:147], v[52:55]
	s_waitcnt lgkmcnt(6)
	v_mfma_f32_16x16x32_bf16 v[44:47], v[128:131], v[152:155], v[44:47]
	v_mfma_f32_16x16x32_bf16 v[36:39], v[136:139], v[152:155], v[36:39]
	s_waitcnt lgkmcnt(5)
	v_mfma_f32_16x16x32_bf16 v[28:31], v[128:131], v[170:173], v[28:31]
	v_mfma_f32_16x16x32_bf16 v[20:23], v[136:139], v[170:173], v[20:23]
	s_waitcnt lgkmcnt(4)
	v_mfma_f32_16x16x32_bf16 v[12:15], v[128:131], v[192:195], v[12:15]
	v_mfma_f32_16x16x32_bf16 v[4:7], v[136:139], v[192:195], v[4:7]
	s_waitcnt lgkmcnt(3)
	v_mfma_f32_16x16x32_bf16 v[60:63], v[132:135], v[148:151], v[60:63]
	v_mfma_f32_16x16x32_bf16 v[52:55], v[140:143], v[148:151], v[52:55]
	s_waitcnt lgkmcnt(2)
	v_mfma_f32_16x16x32_bf16 v[44:47], v[132:135], v[166:169], v[44:47]
	v_mfma_f32_16x16x32_bf16 v[36:39], v[140:143], v[166:169], v[36:39]
	s_waitcnt lgkmcnt(1)
	v_mfma_f32_16x16x32_bf16 v[28:31], v[132:135], v[188:191], v[28:31]
	v_mfma_f32_16x16x32_bf16 v[20:23], v[140:143], v[188:191], v[20:23]
	s_waitcnt lgkmcnt(0)
	v_mfma_f32_16x16x32_bf16 v[12:15], v[132:135], v[202:205], v[12:15]
	v_mfma_f32_16x16x32_bf16 v[4:7], v[140:143], v[202:205], v[4:7]
	s_barrier
	s_add_u32 s50, s50, 0x40080
	s_addc_u32 s51, s51, 0
	s_add_i32 s28, s29, s55
	s_mov_b32 m0, s28
	s_nop 0
	global_load_lds_dwordx4 v176, s[50:51]
	s_add_i32 m0, s28, 0x2000
	s_nop 0
	global_load_lds_dwordx4 v160, s[50:51]
	s_waitcnt vmcnt(6)
	s_barrier
	v_mfma_f32_16x16x32_bf16 v[56:59], v[206:209], v[144:147], v[56:59]
	v_mfma_f32_16x16x32_bf16 v[48:51], v[214:217], v[144:147], v[48:51]
	v_mfma_f32_16x16x32_bf16 v[40:43], v[206:209], v[152:155], v[40:43]
	v_mfma_f32_16x16x32_bf16 v[32:35], v[214:217], v[152:155], v[32:35]
	v_mfma_f32_16x16x32_bf16 v[24:27], v[206:209], v[170:173], v[24:27]
	v_mfma_f32_16x16x32_bf16 v[16:19], v[214:217], v[170:173], v[16:19]
	v_mfma_f32_16x16x32_bf16 v[8:11], v[206:209], v[192:195], v[8:11]
	v_mfma_f32_16x16x32_bf16 v[0:3], v[214:217], v[192:195], v[0:3]
	v_mfma_f32_16x16x32_bf16 v[56:59], v[210:213], v[148:151], v[56:59]
	v_mfma_f32_16x16x32_bf16 v[48:51], v[232:235], v[148:151], v[48:51]
	v_mfma_f32_16x16x32_bf16 v[40:43], v[210:213], v[166:169], v[40:43]
	v_mfma_f32_16x16x32_bf16 v[32:35], v[232:235], v[166:169], v[32:35]
	v_mfma_f32_16x16x32_bf16 v[24:27], v[210:213], v[188:191], v[24:27]
	v_mfma_f32_16x16x32_bf16 v[16:19], v[232:235], v[188:191], v[16:19]
	v_mfma_f32_16x16x32_bf16 v[8:11], v[210:213], v[202:205], v[8:11]
	v_mfma_f32_16x16x32_bf16 v[0:3], v[232:235], v[202:205], v[0:3]
	s_add_i32 s70, s70, 2
	s_add_u32 s6, s6, 0x100
	s_addc_u32 s7, s7, 0
	s_add_u32 s68, s68, 0x100
	s_addc_u32 s69, s69, 0
	s_cmp_lt_u32 s70, 14
	s_barrier
	s_cbranch_scc1 .LBB0_1436
	v_mov_b32_e32 v134, v199
	v_mov_b32_e32 v128, v198
	s_lshl_b32 s4, s4, 8
	s_add_i32 s4, s4, s60
	v_add_u32_e32 v192, s4, v128
	v_lshlrev_b32_e32 v128, 2, v134
	v_ashrrev_i32_e32 v129, 31, v128
	v_ashrrev_i32_e32 v193, 31, v192
	v_add_u32_e32 v190, 16, v192
	v_lshl_add_u64 v[132:133], v[128:129], 2, s[8:9]
	v_lshlrev_b64 v[128:129], 6, v[192:193]
	v_ashrrev_i32_e32 v191, 31, v190
	v_add_u32_e32 v188, 32, v192
	v_lshl_add_u64 v[128:129], v[132:133], 0, v[128:129]
	v_lshlrev_b64 v[130:131], 6, v[190:191]
	v_ashrrev_i32_e32 v189, 31, v188
	v_lshl_add_u64 v[130:131], v[132:133], 0, v[130:131]
	global_load_dwordx4 v[202:205], v[128:129], off
	global_load_dwordx4 v[144:147], v[130:131], off
	v_lshlrev_b64 v[128:129], 6, v[188:189]
	v_add_u32_e32 v174, 48, v192
	v_lshl_add_u64 v[128:129], v[132:133], 0, v[128:129]
	v_ashrrev_i32_e32 v175, 31, v174
	global_load_dwordx4 v[148:151], v[128:129], off
	v_lshlrev_b64 v[128:129], 6, v[174:175]
	v_lshl_add_u64 v[128:129], v[132:133], 0, v[128:129]
	global_load_dwordx4 v[152:155], v[128:129], off
	v_add_u32_e32 v172, 0x80, v192
	v_ashrrev_i32_e32 v173, 31, v172
	v_lshlrev_b64 v[128:129], 6, v[172:173]
	v_lshl_add_u64 v[128:129], v[132:133], 0, v[128:129]
	global_load_dwordx4 v[140:143], v[128:129], off
	v_add_u32_e32 v170, 0x90, v192
	v_ashrrev_i32_e32 v171, 31, v170
	v_lshlrev_b64 v[128:129], 6, v[170:171]
	v_lshl_add_u64 v[128:129], v[132:133], 0, v[128:129]
	global_load_dwordx4 v[128:131], v[128:129], off
	s_lshl_b32 s5, s5, 7
	v_add_u32_e32 v168, 0xa0, v192
	v_add_u32_e32 v166, 0xb0, v192
	s_or_b32 s5, s5, s61
	v_ashrrev_i32_e32 v169, 31, v168
	v_ashrrev_i32_e32 v167, 31, v166
	v_lshl_add_u32 v194, v134, 3, s5
	v_lshlrev_b64 v[134:135], 6, v[168:169]
	v_lshlrev_b64 v[136:137], 6, v[166:167]
	v_lshl_add_u64 v[134:135], v[132:133], 0, v[134:135]
	v_lshl_add_u64 v[132:133], v[132:133], 0, v[136:137]
	global_load_dwordx4 v[136:139], v[134:135], off
	s_nop 0
	global_load_dwordx4 v[132:135], v[132:133], off
	s_mov_b32 s4, 0x358637bd
	v_mov_b64_e32 v[196:197], s[4:5]
	v_ashrrev_i32_e32 v195, 31, v194
	s_mov_b64 s[50:51], s[20:21]
	s_waitcnt vmcnt(0)
	v_mov_b32_e32 v206, v203
	v_mov_b32_e32 v207, v204
	v_mov_b32_e32 v203, v205
	v_mov_b32_e32 v204, v145
	v_mov_b32_e32 v205, v146
	v_mov_b32_e32 v145, v147
	v_pk_add_f32 v[202:203], v[206:207], v[202:203]
	v_mov_b32_e32 v146, v149
	v_mov_b32_e32 v147, v150
	v_mov_b32_e32 v149, v151
	v_mov_b32_e32 v150, v153
	v_mov_b32_e32 v151, v154
	v_mov_b32_e32 v153, v155
	v_pk_add_f32 v[144:145], v[204:205], v[144:145]
	v_mov_b32_e32 v155, v202
	v_pk_add_f32 v[146:147], v[146:147], v[148:149]
	v_pk_add_f32 v[148:149], v[150:151], v[152:153]
	v_mov_b32_e32 v154, v144
	v_mov_b32_e32 v202, v145
	v_mov_b32_e32 v144, v148
	v_mov_b32_e32 v145, v146
	v_mov_b32_e32 v146, v149
	v_pk_add_f32 v[148:149], v[154:155], v[202:203]
	v_pk_add_f32 v[144:145], v[144:145], v[146:147]
	v_mov_b32_e32 v147, v149
	v_mov_b32_e32 v146, v148
	v_mov_b32_e32 v151, v145
	v_mov_b32_e32 v150, v144
	v_mov_b32_e32 v152, v141
	v_mov_b32_e32 v153, v142
	v_mov_b32_e32 v141, v143
	s_waitcnt lgkmcnt(0)
	v_permlane16_swap_b32 v149, v147
	v_permlane16_swap_b32 v148, v146
	v_pk_add_f32 v[142:143], v[148:149], v[146:147]
	v_mov_b32_e32 v147, v143
	v_mov_b32_e32 v146, v142
	v_permlane16_swap_b32 v145, v151
	v_permlane16_swap_b32 v144, v150
	v_pk_add_f32 v[144:145], v[144:145], v[150:151]
	v_mov_b32_e32 v149, v145
	v_mov_b32_e32 v148, v144
	v_mov_b32_e32 v150, v129
	s_waitcnt lgkmcnt(0)
	v_permlane32_swap_b32 v143, v147
	v_permlane32_swap_b32 v142, v146
	v_pk_add_f32 v[142:143], v[142:143], v[146:147]
	v_mov_b32_e32 v151, v130
	v_pk_fma_f32 v[142:143], v[142:143], s[30:31], v[196:197] op_sel_hi:[1,0,0]
	s_waitcnt lgkmcnt(0)
	v_permlane32_swap_b32 v145, v149
	v_permlane32_swap_b32 v144, v148
	v_pk_add_f32 v[144:145], v[144:145], v[148:149]
	v_mul_f32_e32 v129, 0x4b800000, v143
	v_cmp_gt_f32_e32 vcc, s86, v143
	v_pk_fma_f32 v[146:147], v[144:145], s[30:31], v[196:197] op_sel_hi:[1,0,0]
	v_mul_f32_e32 v130, 0x4b800000, v142
	v_cndmask_b32_e32 v129, v143, v129, vcc
	v_rsq_f32_e32 v129, v129
	v_cmp_gt_f32_e64 s[4:5], s86, v142
	v_mul_f32_e32 v144, 0x4b800000, v147
	v_cmp_gt_f32_e64 s[6:7], s86, v147
	v_cndmask_b32_e64 v130, v142, v130, s[4:5]
	v_rsq_f32_e32 v142, v130
	v_cndmask_b32_e64 v130, v147, v144, s[6:7]
	v_rsq_f32_e32 v143, v130
	v_mul_f32_e32 v130, 0x45800000, v129
	v_cndmask_b32_e32 v144, v129, v130, vcc
	v_mov_b32_e32 v129, v131
	v_pk_add_f32 v[140:141], v[152:153], v[140:141]
	v_pk_add_f32 v[128:129], v[150:151], v[128:129]
	v_mov_b32_e32 v131, v140
	v_mov_b32_e32 v130, v128
	v_mov_b32_e32 v140, v129
	v_pk_add_f32 v[128:129], v[130:131], v[140:141]
	v_mov_b32_e32 v131, v129
	v_mov_b32_e32 v130, v128
	v_mul_f32_e32 v145, 0x45800000, v142
	v_cndmask_b32_e64 v142, v142, v145, s[4:5]
	v_mul_f32_e32 v140, 0x4b800000, v146
	v_cmp_gt_f32_e32 vcc, s86, v146
	s_waitcnt lgkmcnt(0)
	v_permlane16_swap_b32 v129, v131
	v_permlane16_swap_b32 v128, v130
	v_pk_add_f32 v[128:129], v[128:129], v[130:131]
	v_mov_b32_e32 v131, v129
	v_mov_b32_e32 v130, v128
	v_cndmask_b32_e32 v140, v146, v140, vcc
	v_rsq_f32_e32 v141, v140
	v_mul_f32_e32 v140, 0x45800000, v143
	v_cndmask_b32_e64 v140, v143, v140, s[6:7]
	s_waitcnt lgkmcnt(0)
	v_permlane32_swap_b32 v129, v131
	v_permlane32_swap_b32 v128, v130
	v_pk_add_f32 v[128:129], v[128:129], v[130:131]
	v_mov_b32_e32 v131, v138
	v_pk_fma_f32 v[128:129], v[128:129], s[30:31], v[196:197] op_sel_hi:[1,0,0]
	v_mul_f32_e32 v143, 0x45800000, v141
	v_mul_f32_e32 v130, 0x4b800000, v129
	v_cmp_gt_f32_e64 s[4:5], s86, v129
	v_cmp_gt_f32_e64 s[6:7], s86, v128
	v_pk_mul_f32 v[110:111], v[110:111], v[142:143] op_sel_hi:[1,0]
	v_cndmask_b32_e64 v129, v129, v130, s[4:5]
	v_mov_b32_e32 v130, v137
	v_mov_b32_e32 v137, v139
	v_pk_add_f32 v[130:131], v[130:131], v[136:137]
	v_mov_b32_e32 v136, v133
	v_mov_b32_e32 v137, v134
	v_mov_b32_e32 v133, v135
	v_pk_add_f32 v[132:133], v[136:137], v[132:133]
	v_mov_b32_e32 v135, v130
	v_mov_b32_e32 v134, v132
	v_mov_b32_e32 v130, v133
	v_pk_add_f32 v[130:131], v[134:135], v[130:131]
	v_mov_b32_e32 v133, v131
	v_mov_b32_e32 v132, v130
	v_rsq_f32_e32 v145, v129
	v_mul_f32_e32 v129, 0x4b800000, v128
	v_cndmask_b32_e64 v128, v128, v129, s[6:7]
	v_rsq_f32_e32 v135, v128
	s_waitcnt lgkmcnt(0)
	v_permlane16_swap_b32 v131, v133
	v_permlane16_swap_b32 v130, v132
	v_pk_add_f32 v[128:129], v[130:131], v[132:133]
	v_mov_b32_e32 v131, v129
	v_mov_b32_e32 v130, v128
	v_pk_mul_f32 v[126:127], v[126:127], v[144:145] op_sel_hi:[1,0]
	v_pk_mul_f32 v[122:123], v[122:123], v[144:145] op_sel_hi:[1,0]
	v_pk_mul_f32 v[116:117], v[116:117], v[144:145] op_sel_hi:[1,0]
	v_pk_mul_f32 v[124:125], v[124:125], v[144:145] op_sel_hi:[1,0]
	v_pk_mul_f32 v[138:139], v[126:127], s[44:45] op_sel_hi:[1,0]
	v_pk_mul_f32 v[120:121], v[120:121], v[144:145] op_sel_hi:[1,0]
	v_pk_mul_f32 v[122:123], v[126:127], v[122:123]
	v_pk_mul_f32 v[118:119], v[118:119], v[144:145] op_sel_hi:[1,0]
	v_pk_mul_f32 v[126:127], v[116:117], s[44:45] op_sel_hi:[1,0]
	v_pk_mul_f32 v[146:147], v[124:125], s[44:45] op_sel_hi:[1,0]
	v_pk_mul_f32 v[120:121], v[124:125], v[120:121]
	v_pk_mul_f32 v[124:125], v[118:119], s[44:45] op_sel_hi:[1,0]
	v_exp_f32_e32 v126, v126
	v_exp_f32_e32 v127, v127
	s_waitcnt lgkmcnt(0)
	v_permlane32_swap_b32 v129, v131
	v_permlane32_swap_b32 v128, v130
	v_pk_add_f32 v[128:129], v[128:129], v[130:131]
	v_exp_f32_e32 v146, v146
	v_exp_f32_e32 v138, v138
	v_exp_f32_e32 v139, v139
	v_exp_f32_e32 v147, v147
	v_exp_f32_e32 v124, v124
	v_exp_f32_e32 v125, v125
	v_pk_fma_f32 v[128:129], v[128:129], s[30:31], v[196:197] op_sel_hi:[1,0,0]
	v_cndmask_b32_e32 v136, v141, v143, vcc
	v_mul_f32_e32 v132, 0x45800000, v145
	v_mul_f32_e32 v130, 0x4b800000, v129
	v_cmp_gt_f32_e32 vcc, s86, v129
	v_cndmask_b32_e64 v134, v145, v132, s[4:5]
	v_cmp_gt_f32_e64 s[4:5], s86, v128
	v_cndmask_b32_e32 v129, v129, v130, vcc
	v_mul_f32_e32 v130, 0x4b800000, v128
	v_pk_add_f32 v[126:127], v[126:127], 1.0 op_sel_hi:[1,0]
	v_rsq_f32_e32 v129, v129
	v_cndmask_b32_e64 v128, v128, v130, s[4:5]
	v_pk_add_f32 v[138:139], v[138:139], 1.0 op_sel_hi:[1,0]
	v_pk_add_f32 v[146:147], v[146:147], 1.0 op_sel_hi:[1,0]
	v_pk_add_f32 v[124:125], v[124:125], 1.0 op_sel_hi:[1,0]
	v_rcp_f32_e32 v126, v126
	v_rcp_f32_e32 v127, v127
	v_rsq_f32_e32 v128, v128
	v_rcp_f32_e32 v146, v146
	v_rcp_f32_e32 v138, v138
	v_rcp_f32_e32 v139, v139
	v_rcp_f32_e32 v147, v147
	v_rcp_f32_e32 v124, v124
	v_rcp_f32_e32 v125, v125
	v_pk_mul_f32 v[112:113], v[112:113], v[144:145] op_sel_hi:[1,0]
	v_pk_mul_f32 v[114:115], v[114:115], v[144:145] op_sel_hi:[1,0]
	v_pk_mul_f32 v[112:113], v[116:117], v[112:113]
	v_mul_f32_e32 v130, 0x45800000, v129
	v_pk_mul_f32 v[114:115], v[118:119], v[114:115]
	v_pk_mul_f32 v[112:113], v[112:113], v[126:127]
	v_cndmask_b32_e32 v130, v129, v130, vcc
	v_mul_f32_e32 v129, 0x45800000, v128
	v_pk_mul_f32 v[122:123], v[122:123], v[138:139]
	v_pk_mul_f32 v[120:121], v[120:121], v[146:147]
	v_pk_mul_f32 v[114:115], v[114:115], v[124:125]
	v_cvt_pk_bf16_f32 v116, v120, v121
	v_cvt_pk_bf16_f32 v117, v122, v123
	v_cvt_pk_bf16_f32 v118, v112, v113
	v_mov_b64_e32 v[112:113], s[10:11]
	v_cndmask_b32_e64 v128, v128, v129, s[4:5]
	v_cvt_pk_bf16_f32 v119, v114, v115
	v_mad_i64_i32 v[120:121], s[4:5], v192, s35, v[112:113]
	v_lshlrev_b64 v[114:115], 1, v[194:195]
	v_lshl_add_u64 v[120:121], v[120:121], 0, v[114:115]
	v_pk_mul_f32 v[108:109], v[108:109], v[142:143] op_sel_hi:[1,0]
	v_pk_mul_f32 v[106:107], v[106:107], v[142:143] op_sel_hi:[1,0]
	v_pk_mul_f32 v[104:105], v[104:105], v[142:143] op_sel_hi:[1,0]
	v_pk_mul_f32 v[102:103], v[102:103], v[142:143] op_sel_hi:[1,0]
	v_pk_mul_f32 v[100:101], v[100:101], v[142:143] op_sel_hi:[1,0]
	global_store_dwordx4 v[120:121], v[116:119], off
	v_pk_mul_f32 v[104:105], v[108:109], v[104:105]
	v_pk_mul_f32 v[106:107], v[110:111], v[106:107]
	v_pk_mul_f32 v[116:117], v[110:111], s[44:45] op_sel_hi:[1,0]
	v_pk_mul_f32 v[118:119], v[108:109], s[44:45] op_sel_hi:[1,0]
	v_pk_mul_f32 v[108:109], v[102:103], s[44:45] op_sel_hi:[1,0]
	v_pk_mul_f32 v[110:111], v[100:101], s[44:45] op_sel_hi:[1,0]
	v_exp_f32_e32 v108, v108
	v_exp_f32_e32 v110, v110
	v_exp_f32_e32 v109, v109
	v_exp_f32_e32 v111, v111
	v_exp_f32_e32 v118, v118
	v_exp_f32_e32 v116, v116
	v_exp_f32_e32 v117, v117
	v_exp_f32_e32 v119, v119
	v_pk_add_f32 v[108:109], v[108:109], 1.0 op_sel_hi:[1,0]
	v_pk_add_f32 v[110:111], v[110:111], 1.0 op_sel_hi:[1,0]
	v_pk_add_f32 v[116:117], v[116:117], 1.0 op_sel_hi:[1,0]
	v_pk_add_f32 v[118:119], v[118:119], 1.0 op_sel_hi:[1,0]
	v_rcp_f32_e32 v110, v110
	v_rcp_f32_e32 v108, v108
	v_rcp_f32_e32 v109, v109
	v_rcp_f32_e32 v111, v111
	v_rcp_f32_e32 v118, v118
	v_rcp_f32_e32 v116, v116
	v_rcp_f32_e32 v117, v117
	v_rcp_f32_e32 v119, v119
	v_pk_mul_f32 v[98:99], v[98:99], v[142:143] op_sel_hi:[1,0]
	v_pk_mul_f32 v[96:97], v[96:97], v[142:143] op_sel_hi:[1,0]
	v_pk_mul_f32 v[98:99], v[102:103], v[98:99]
	v_pk_mul_f32 v[96:97], v[100:101], v[96:97]
	v_pk_mul_f32 v[100:101], v[98:99], v[108:109]
	v_pk_mul_f32 v[98:99], v[96:97], v[110:111]
	v_pk_mul_f32 v[106:107], v[106:107], v[116:117]
	v_pk_mul_f32 v[104:105], v[104:105], v[118:119]
	v_pk_mul_f32 v[94:95], v[94:95], v[140:141] op_sel_hi:[1,0]
	v_cvt_pk_bf16_f32 v96, v104, v105
	v_cvt_pk_bf16_f32 v97, v106, v107
	v_cvt_pk_bf16_f32 v98, v98, v99
	v_cvt_pk_bf16_f32 v99, v100, v101
	v_mad_i64_i32 v[100:101], s[4:5], v190, s35, v[112:113]
	v_lshl_add_u64 v[100:101], v[100:101], 0, v[114:115]
	v_pk_mul_f32 v[92:93], v[92:93], v[140:141] op_sel_hi:[1,0]
	v_pk_mul_f32 v[90:91], v[90:91], v[140:141] op_sel_hi:[1,0]
	v_pk_mul_f32 v[88:89], v[88:89], v[140:141] op_sel_hi:[1,0]
	v_pk_mul_f32 v[86:87], v[86:87], v[140:141] op_sel_hi:[1,0]
	v_pk_mul_f32 v[84:85], v[84:85], v[140:141] op_sel_hi:[1,0]
	global_store_dwordx4 v[100:101], v[96:99], off
	v_pk_mul_f32 v[88:89], v[92:93], v[88:89]
	v_pk_mul_f32 v[90:91], v[94:95], v[90:91]
	v_pk_mul_f32 v[96:97], v[94:95], s[44:45] op_sel_hi:[1,0]
	v_pk_mul_f32 v[98:99], v[92:93], s[44:45] op_sel_hi:[1,0]
	v_pk_mul_f32 v[92:93], v[86:87], s[44:45] op_sel_hi:[1,0]
	v_pk_mul_f32 v[94:95], v[84:85], s[44:45] op_sel_hi:[1,0]
	v_exp_f32_e32 v92, v92
	v_exp_f32_e32 v94, v94
	v_exp_f32_e32 v93, v93
	v_exp_f32_e32 v95, v95
	v_exp_f32_e32 v98, v98
	v_exp_f32_e32 v96, v96
	v_exp_f32_e32 v97, v97
	v_exp_f32_e32 v99, v99
	v_pk_add_f32 v[92:93], v[92:93], 1.0 op_sel_hi:[1,0]
	v_pk_add_f32 v[94:95], v[94:95], 1.0 op_sel_hi:[1,0]
	v_pk_add_f32 v[96:97], v[96:97], 1.0 op_sel_hi:[1,0]
	v_pk_add_f32 v[98:99], v[98:99], 1.0 op_sel_hi:[1,0]
	v_rcp_f32_e32 v94, v94
	v_rcp_f32_e32 v92, v92
	v_rcp_f32_e32 v93, v93
	v_rcp_f32_e32 v95, v95
	v_rcp_f32_e32 v98, v98
	v_rcp_f32_e32 v96, v96
	v_rcp_f32_e32 v97, v97
	v_rcp_f32_e32 v99, v99
	v_pk_mul_f32 v[82:83], v[82:83], v[140:141] op_sel_hi:[1,0]
	v_pk_mul_f32 v[80:81], v[80:81], v[140:141] op_sel_hi:[1,0]
	v_pk_mul_f32 v[82:83], v[86:87], v[82:83]
	v_pk_mul_f32 v[80:81], v[84:85], v[80:81]
	v_pk_mul_f32 v[84:85], v[82:83], v[92:93]
	v_pk_mul_f32 v[82:83], v[80:81], v[94:95]
	v_pk_mul_f32 v[90:91], v[90:91], v[96:97]
	v_pk_mul_f32 v[88:89], v[88:89], v[98:99]
	v_pk_mul_f32 v[78:79], v[78:79], v[136:137] op_sel_hi:[1,0]
	v_cvt_pk_bf16_f32 v80, v88, v89
	v_cvt_pk_bf16_f32 v81, v90, v91
	v_cvt_pk_bf16_f32 v82, v82, v83
	v_cvt_pk_bf16_f32 v83, v84, v85
	v_mad_i64_i32 v[84:85], s[4:5], v188, s35, v[112:113]
	v_lshl_add_u64 v[84:85], v[84:85], 0, v[114:115]
	v_pk_mul_f32 v[76:77], v[76:77], v[136:137] op_sel_hi:[1,0]
	v_pk_mul_f32 v[74:75], v[74:75], v[136:137] op_sel_hi:[1,0]
	v_pk_mul_f32 v[72:73], v[72:73], v[136:137] op_sel_hi:[1,0]
	v_pk_mul_f32 v[70:71], v[70:71], v[136:137] op_sel_hi:[1,0]
	v_pk_mul_f32 v[68:69], v[68:69], v[136:137] op_sel_hi:[1,0]
	global_store_dwordx4 v[84:85], v[80:83], off
	v_pk_mul_f32 v[72:73], v[76:77], v[72:73]
	v_pk_mul_f32 v[74:75], v[78:79], v[74:75]
	v_pk_mul_f32 v[80:81], v[78:79], s[44:45] op_sel_hi:[1,0]
	v_pk_mul_f32 v[82:83], v[76:77], s[44:45] op_sel_hi:[1,0]
	v_pk_mul_f32 v[76:77], v[70:71], s[44:45] op_sel_hi:[1,0]
	v_pk_mul_f32 v[78:79], v[68:69], s[44:45] op_sel_hi:[1,0]
	v_exp_f32_e32 v76, v76
	v_exp_f32_e32 v78, v78
	v_exp_f32_e32 v77, v77
	v_exp_f32_e32 v79, v79
	v_exp_f32_e32 v82, v82
	v_exp_f32_e32 v80, v80
	v_exp_f32_e32 v81, v81
	v_exp_f32_e32 v83, v83
	v_pk_add_f32 v[76:77], v[76:77], 1.0 op_sel_hi:[1,0]
	v_pk_add_f32 v[78:79], v[78:79], 1.0 op_sel_hi:[1,0]
	v_pk_add_f32 v[80:81], v[80:81], 1.0 op_sel_hi:[1,0]
	v_pk_add_f32 v[82:83], v[82:83], 1.0 op_sel_hi:[1,0]
	v_rcp_f32_e32 v78, v78
	v_rcp_f32_e32 v76, v76
	v_rcp_f32_e32 v77, v77
	v_rcp_f32_e32 v79, v79
	v_rcp_f32_e32 v82, v82
	v_rcp_f32_e32 v80, v80
	v_rcp_f32_e32 v81, v81
	v_rcp_f32_e32 v83, v83
	v_pk_mul_f32 v[66:67], v[66:67], v[136:137] op_sel_hi:[1,0]
	v_pk_mul_f32 v[64:65], v[64:65], v[136:137] op_sel_hi:[1,0]
	v_pk_mul_f32 v[66:67], v[70:71], v[66:67]
	v_pk_mul_f32 v[64:65], v[68:69], v[64:65]
	v_pk_mul_f32 v[68:69], v[66:67], v[76:77]
	v_pk_mul_f32 v[66:67], v[64:65], v[78:79]
	v_pk_mul_f32 v[74:75], v[74:75], v[80:81]
	v_pk_mul_f32 v[72:73], v[72:73], v[82:83]
	v_pk_mul_f32 v[62:63], v[62:63], v[134:135] op_sel_hi:[1,0]
	v_cvt_pk_bf16_f32 v64, v72, v73
	v_cvt_pk_bf16_f32 v65, v74, v75
	v_cvt_pk_bf16_f32 v66, v66, v67
	v_cvt_pk_bf16_f32 v67, v68, v69
	v_mad_i64_i32 v[68:69], s[4:5], v174, s35, v[112:113]
	v_lshl_add_u64 v[68:69], v[68:69], 0, v[114:115]
	v_pk_mul_f32 v[60:61], v[60:61], v[134:135] op_sel_hi:[1,0]
	v_pk_mul_f32 v[58:59], v[58:59], v[134:135] op_sel_hi:[1,0]
	v_pk_mul_f32 v[56:57], v[56:57], v[134:135] op_sel_hi:[1,0]
	v_pk_mul_f32 v[54:55], v[54:55], v[134:135] op_sel_hi:[1,0]
	v_pk_mul_f32 v[52:53], v[52:53], v[134:135] op_sel_hi:[1,0]
	global_store_dwordx4 v[68:69], v[64:67], off
	v_pk_mul_f32 v[56:57], v[60:61], v[56:57]
	v_pk_mul_f32 v[58:59], v[62:63], v[58:59]
	v_pk_mul_f32 v[64:65], v[62:63], s[44:45] op_sel_hi:[1,0]
	v_pk_mul_f32 v[66:67], v[60:61], s[44:45] op_sel_hi:[1,0]
	v_pk_mul_f32 v[60:61], v[54:55], s[44:45] op_sel_hi:[1,0]
	v_pk_mul_f32 v[62:63], v[52:53], s[44:45] op_sel_hi:[1,0]
	v_exp_f32_e32 v60, v60
	v_exp_f32_e32 v62, v62
	v_exp_f32_e32 v61, v61
	v_exp_f32_e32 v63, v63
	v_exp_f32_e32 v66, v66
	v_exp_f32_e32 v64, v64
	v_exp_f32_e32 v65, v65
	v_exp_f32_e32 v67, v67
	v_pk_add_f32 v[60:61], v[60:61], 1.0 op_sel_hi:[1,0]
	v_pk_add_f32 v[62:63], v[62:63], 1.0 op_sel_hi:[1,0]
	v_pk_add_f32 v[64:65], v[64:65], 1.0 op_sel_hi:[1,0]
	v_pk_add_f32 v[66:67], v[66:67], 1.0 op_sel_hi:[1,0]
	v_rcp_f32_e32 v62, v62
	v_rcp_f32_e32 v60, v60
	v_rcp_f32_e32 v61, v61
	v_rcp_f32_e32 v63, v63
	v_rcp_f32_e32 v66, v66
	v_rcp_f32_e32 v64, v64
	v_rcp_f32_e32 v65, v65
	v_rcp_f32_e32 v67, v67
	v_pk_mul_f32 v[50:51], v[50:51], v[134:135] op_sel_hi:[1,0]
	v_pk_mul_f32 v[48:49], v[48:49], v[134:135] op_sel_hi:[1,0]
	v_pk_mul_f32 v[50:51], v[54:55], v[50:51]
	v_pk_mul_f32 v[48:49], v[52:53], v[48:49]
	v_mul_f32_e32 v132, 0x45800000, v135
	v_pk_mul_f32 v[52:53], v[50:51], v[60:61]
	v_pk_mul_f32 v[50:51], v[48:49], v[62:63]
	v_cndmask_b32_e64 v132, v135, v132, s[6:7]
	v_pk_mul_f32 v[58:59], v[58:59], v[64:65]
	v_pk_mul_f32 v[56:57], v[56:57], v[66:67]
	v_pk_mul_f32 v[46:47], v[46:47], v[132:133] op_sel_hi:[1,0]
	v_cvt_pk_bf16_f32 v48, v56, v57
	v_cvt_pk_bf16_f32 v49, v58, v59
	v_cvt_pk_bf16_f32 v50, v50, v51
	v_cvt_pk_bf16_f32 v51, v52, v53
	v_mad_i64_i32 v[52:53], s[4:5], v172, s35, v[112:113]
	v_lshl_add_u64 v[52:53], v[52:53], 0, v[114:115]
	v_pk_mul_f32 v[44:45], v[44:45], v[132:133] op_sel_hi:[1,0]
	v_pk_mul_f32 v[42:43], v[42:43], v[132:133] op_sel_hi:[1,0]
	v_pk_mul_f32 v[40:41], v[40:41], v[132:133] op_sel_hi:[1,0]
	v_pk_mul_f32 v[38:39], v[38:39], v[132:133] op_sel_hi:[1,0]
	v_pk_mul_f32 v[36:37], v[36:37], v[132:133] op_sel_hi:[1,0]
	global_store_dwordx4 v[52:53], v[48:51], off
	v_pk_mul_f32 v[40:41], v[44:45], v[40:41]
	v_pk_mul_f32 v[42:43], v[46:47], v[42:43]
	v_pk_mul_f32 v[48:49], v[46:47], s[44:45] op_sel_hi:[1,0]
	v_pk_mul_f32 v[50:51], v[44:45], s[44:45] op_sel_hi:[1,0]
	v_pk_mul_f32 v[44:45], v[38:39], s[44:45] op_sel_hi:[1,0]
	v_pk_mul_f32 v[46:47], v[36:37], s[44:45] op_sel_hi:[1,0]
	v_exp_f32_e32 v44, v44
	v_exp_f32_e32 v46, v46
	v_exp_f32_e32 v45, v45
	v_exp_f32_e32 v47, v47
	v_exp_f32_e32 v50, v50
	v_exp_f32_e32 v48, v48
	v_exp_f32_e32 v49, v49
	v_exp_f32_e32 v51, v51
	v_pk_add_f32 v[44:45], v[44:45], 1.0 op_sel_hi:[1,0]
	v_pk_add_f32 v[46:47], v[46:47], 1.0 op_sel_hi:[1,0]
	v_pk_add_f32 v[48:49], v[48:49], 1.0 op_sel_hi:[1,0]
	v_pk_add_f32 v[50:51], v[50:51], 1.0 op_sel_hi:[1,0]
	v_rcp_f32_e32 v46, v46
	v_rcp_f32_e32 v44, v44
	v_rcp_f32_e32 v45, v45
	v_rcp_f32_e32 v47, v47
	v_rcp_f32_e32 v50, v50
	v_rcp_f32_e32 v48, v48
	v_rcp_f32_e32 v49, v49
	v_rcp_f32_e32 v51, v51
	v_pk_mul_f32 v[34:35], v[34:35], v[132:133] op_sel_hi:[1,0]
	v_pk_mul_f32 v[32:33], v[32:33], v[132:133] op_sel_hi:[1,0]
	v_pk_mul_f32 v[34:35], v[38:39], v[34:35]
	v_pk_mul_f32 v[32:33], v[36:37], v[32:33]
	v_pk_mul_f32 v[36:37], v[34:35], v[44:45]
	v_pk_mul_f32 v[34:35], v[32:33], v[46:47]
	v_pk_mul_f32 v[42:43], v[42:43], v[48:49]
	v_pk_mul_f32 v[40:41], v[40:41], v[50:51]
	v_pk_mul_f32 v[30:31], v[30:31], v[130:131] op_sel_hi:[1,0]
	v_cvt_pk_bf16_f32 v32, v40, v41
	v_cvt_pk_bf16_f32 v33, v42, v43
	v_cvt_pk_bf16_f32 v34, v34, v35
	v_cvt_pk_bf16_f32 v35, v36, v37
	v_mad_i64_i32 v[36:37], s[4:5], v170, s35, v[112:113]
	v_lshl_add_u64 v[36:37], v[36:37], 0, v[114:115]
	v_pk_mul_f32 v[28:29], v[28:29], v[130:131] op_sel_hi:[1,0]
	v_pk_mul_f32 v[26:27], v[26:27], v[130:131] op_sel_hi:[1,0]
	v_pk_mul_f32 v[24:25], v[24:25], v[130:131] op_sel_hi:[1,0]
	v_pk_mul_f32 v[22:23], v[22:23], v[130:131] op_sel_hi:[1,0]
	v_pk_mul_f32 v[20:21], v[20:21], v[130:131] op_sel_hi:[1,0]
	global_store_dwordx4 v[36:37], v[32:35], off
	v_pk_mul_f32 v[24:25], v[28:29], v[24:25]
	v_pk_mul_f32 v[26:27], v[30:31], v[26:27]
	v_pk_mul_f32 v[32:33], v[30:31], s[44:45] op_sel_hi:[1,0]
	v_pk_mul_f32 v[34:35], v[28:29], s[44:45] op_sel_hi:[1,0]
	v_pk_mul_f32 v[28:29], v[22:23], s[44:45] op_sel_hi:[1,0]
	v_pk_mul_f32 v[30:31], v[20:21], s[44:45] op_sel_hi:[1,0]
	v_exp_f32_e32 v28, v28
	v_exp_f32_e32 v30, v30
	v_exp_f32_e32 v29, v29
	v_exp_f32_e32 v31, v31
	v_exp_f32_e32 v34, v34
	v_exp_f32_e32 v32, v32
	v_exp_f32_e32 v33, v33
	v_exp_f32_e32 v35, v35
	v_pk_add_f32 v[28:29], v[28:29], 1.0 op_sel_hi:[1,0]
	v_pk_add_f32 v[30:31], v[30:31], 1.0 op_sel_hi:[1,0]
	v_pk_add_f32 v[32:33], v[32:33], 1.0 op_sel_hi:[1,0]
	v_pk_add_f32 v[34:35], v[34:35], 1.0 op_sel_hi:[1,0]
	v_rcp_f32_e32 v30, v30
	v_rcp_f32_e32 v28, v28
	v_rcp_f32_e32 v29, v29
	v_rcp_f32_e32 v31, v31
	v_rcp_f32_e32 v34, v34
	v_rcp_f32_e32 v32, v32
	v_rcp_f32_e32 v33, v33
	v_rcp_f32_e32 v35, v35
	v_pk_mul_f32 v[18:19], v[18:19], v[130:131] op_sel_hi:[1,0]
	v_pk_mul_f32 v[16:17], v[16:17], v[130:131] op_sel_hi:[1,0]
	v_pk_mul_f32 v[18:19], v[22:23], v[18:19]
	v_pk_mul_f32 v[16:17], v[20:21], v[16:17]
	v_pk_mul_f32 v[20:21], v[18:19], v[28:29]
	v_pk_mul_f32 v[18:19], v[16:17], v[30:31]
	v_pk_mul_f32 v[26:27], v[26:27], v[32:33]
	v_pk_mul_f32 v[24:25], v[24:25], v[34:35]
	v_pk_mul_f32 v[14:15], v[14:15], v[128:129] op_sel_hi:[1,0]
	v_cvt_pk_bf16_f32 v16, v24, v25
	v_cvt_pk_bf16_f32 v17, v26, v27
	v_cvt_pk_bf16_f32 v18, v18, v19
	v_cvt_pk_bf16_f32 v19, v20, v21
	v_mad_i64_i32 v[20:21], s[4:5], v168, s35, v[112:113]
	v_lshl_add_u64 v[20:21], v[20:21], 0, v[114:115]
	v_pk_mul_f32 v[12:13], v[12:13], v[128:129] op_sel_hi:[1,0]
	v_pk_mul_f32 v[10:11], v[10:11], v[128:129] op_sel_hi:[1,0]
	v_pk_mul_f32 v[8:9], v[8:9], v[128:129] op_sel_hi:[1,0]
	v_pk_mul_f32 v[6:7], v[6:7], v[128:129] op_sel_hi:[1,0]
	v_pk_mul_f32 v[4:5], v[4:5], v[128:129] op_sel_hi:[1,0]
	global_store_dwordx4 v[20:21], v[16:19], off
	v_pk_mul_f32 v[8:9], v[12:13], v[8:9]
	v_pk_mul_f32 v[10:11], v[14:15], v[10:11]
	v_pk_mul_f32 v[16:17], v[14:15], s[44:45] op_sel_hi:[1,0]
	v_pk_mul_f32 v[18:19], v[12:13], s[44:45] op_sel_hi:[1,0]
	v_pk_mul_f32 v[12:13], v[6:7], s[44:45] op_sel_hi:[1,0]
	v_pk_mul_f32 v[14:15], v[4:5], s[44:45] op_sel_hi:[1,0]
	v_exp_f32_e32 v12, v12
	v_exp_f32_e32 v14, v14
	v_exp_f32_e32 v13, v13
	v_exp_f32_e32 v15, v15
	v_exp_f32_e32 v18, v18
	v_exp_f32_e32 v16, v16
	v_exp_f32_e32 v17, v17
	v_exp_f32_e32 v19, v19
	v_pk_add_f32 v[12:13], v[12:13], 1.0 op_sel_hi:[1,0]
	v_pk_add_f32 v[14:15], v[14:15], 1.0 op_sel_hi:[1,0]
	v_pk_add_f32 v[16:17], v[16:17], 1.0 op_sel_hi:[1,0]
	v_pk_add_f32 v[18:19], v[18:19], 1.0 op_sel_hi:[1,0]
	v_rcp_f32_e32 v14, v14
	v_rcp_f32_e32 v12, v12
	v_rcp_f32_e32 v13, v13
	v_rcp_f32_e32 v15, v15
	v_rcp_f32_e32 v18, v18
	v_rcp_f32_e32 v16, v16
	v_rcp_f32_e32 v17, v17
	v_rcp_f32_e32 v19, v19
	v_pk_mul_f32 v[2:3], v[2:3], v[128:129] op_sel_hi:[1,0]
	v_pk_mul_f32 v[0:1], v[0:1], v[128:129] op_sel_hi:[1,0]
	v_pk_mul_f32 v[2:3], v[6:7], v[2:3]
	v_pk_mul_f32 v[0:1], v[4:5], v[0:1]
	v_pk_mul_f32 v[4:5], v[2:3], v[12:13]
	v_pk_mul_f32 v[2:3], v[0:1], v[14:15]
	v_pk_mul_f32 v[10:11], v[10:11], v[16:17]
	v_pk_mul_f32 v[8:9], v[8:9], v[18:19]
	s_andn2_b64 vcc, exec, s[2:3]
	v_cvt_pk_bf16_f32 v0, v8, v9
	v_cvt_pk_bf16_f32 v1, v10, v11
	v_cvt_pk_bf16_f32 v2, v2, v3
	v_cvt_pk_bf16_f32 v3, v4, v5
	v_mad_i64_i32 v[4:5], s[4:5], v166, s35, v[112:113]
	v_lshl_add_u64 v[4:5], v[4:5], 0, v[114:115]
	s_mov_b32 s4, s16
	s_mov_b32 s5, s12
	s_mov_b64 s[6:7], s[18:19]
	global_store_dwordx4 v[4:5], v[0:3], off
	s_cbranch_vccnz .LBB0_1429
	s_waitcnt vmcnt(0)
	s_cmpk_gt_u32 s24, 0xff
	s_cbranch_scc1 .LBB0_1440
	s_barrier
